# WFR: P0 forget-gate projection keeps 23 of the 64 per-lane weight vectors in v[160:251] for the whole chunk loop (ds_reads deleted, lgkmcnt waits recounted)
# speedup vs baseline: 1.0072x; 1.0011x over previous
; #define LAS __attribute__((address_space(3)))
; __device__ __forceinline__ void p0_phase(const Args& a, LAS unsigned char* lds, int tid, int lane, int wave) {
;     ...
;     const float* gmix = a.in[7]; const float* bfg = a.in[9];
;     float gm[16];
; #pragma unroll
;     for (int j = 0; j < 16; ++j) gm[j] = gmix[lane + 64 * j];
;     bf16_t* XN = (bf16_t*)(ws + WS_XN);
;     for (int c = blockIdx.x; c < 784; c += gridDim.x) {
;     ...
;                     const LAS f32x4* wp = (const LAS f32x4*)(wfl + (lane + 64 * j) * 16);
; #pragma unroll
;                     for (int q = 0; q < 4; ++q) { const f32x4 w = wp[q]; f[4 * q + 0] += xn * w[0]; f[4 * q + 1] += xn * w[1]; f[4 * q + 2] += xn * w[2]; f[4 * q + 3] += xn * w[3]; } }
.LBB0_25:
	s_or_b64 exec, exec, s[0:1]
	s_cmpk_lt_i32 s44, 0x310
	s_waitcnt lgkmcnt(0)
	s_barrier
	s_cbranch_scc0 .LBB0_53
	v_lshlrev_b32_e32 v1, 2, v132
	v_or_b32_e32 v0, 0x3c0, v134
	global_load_dword v9, v1, s[66:67]
	global_load_dword v34, v1, s[66:67] offset:256
	global_load_dword v35, v1, s[66:67] offset:512
	global_load_dword v36, v1, s[66:67] offset:768
	global_load_dword v37, v1, s[66:67] offset:1024
	global_load_dword v38, v1, s[66:67] offset:1280
	global_load_dword v39, v1, s[66:67] offset:1536
	global_load_dword v40, v1, s[66:67] offset:1792
	v_lshlrev_b32_e32 v3, 2, v0
	global_load_dword v41, v1, s[66:67] offset:2048
	global_load_dword v42, v1, s[66:67] offset:2304
	global_load_dword v43, v1, s[66:67] offset:2560
	global_load_dword v44, v1, s[66:67] offset:2816
	global_load_dword v45, v1, s[66:67] offset:3072
	global_load_dword v46, v1, s[66:67] offset:3328
	global_load_dword v47, v1, s[66:67] offset:3584
	global_load_dword v48, v3, s[66:67]
	v_mov_b32_e32 v5, 0
	s_add_i32 s4, 0, 0x21000
	v_readlane_b32 s0, v254, 21
	v_lshlrev_b32_e32 v4, 1, v132
	v_lshl_add_u32 v50, v2, 2, s4
	s_lshl_b32 s48, s0, 3
	v_lshl_add_u64 v[2:3], s[88:89], 0, v[4:5]
	s_mov_b64 s[0:1], 0x3000000
	v_lshl_add_u64 v[6:7], v[2:3], 0, s[0:1]
	v_and_b32_e32 v52, 15, v134
	v_lshrrev_b32_e32 v19, 4, v134
	s_movk_i32 s0, 0x100
	v_lshlrev_b32_e32 v14, 2, v134
	v_cmp_gt_u32_e64 s[2:3], s0, v134
	v_lshlrev_b32_e32 v2, 8, v19
	v_lshlrev_b32_e32 v4, 2, v52
	s_add_i32 s0, 0, 0x22000
	v_add3_u32 v53, s4, v2, v4
	v_add_u32_e32 v54, s0, v14
	v_add_u32_e32 v55, s0, v4
	s_add_u32 s0, s88, 0x400000
	v_mul_u32_u24_e32 v4, 0x4400, v52
	s_addc_u32 s1, s89, 0
	v_lshlrev_b32_e32 v4, 2, v4
	v_writelane_b32 v254, s0, 26
	v_lshl_add_u64 v[12:13], s[88:89], 0, v[4:5]
	v_and_b32_e32 v4, 0x3f0, v134
	v_writelane_b32 v254, s1, 27
	v_lshl_add_u64 v[12:13], v[12:13], 0, v[4:5]
	s_mov_b64 s[0:1], 0x200000
	v_lshl_add_u64 v[12:13], v[12:13], 0, s[0:1]
	s_add_u32 s0, s88, 0x148000
	s_addc_u32 s1, s89, 0
	v_writelane_b32 v254, s0, 28
	v_mul_u32_u24_e32 v57, 0x50, v132
	v_mov_b32_e32 v133, v5
	v_writelane_b32 v254, s1, 29
	s_add_u32 s0, s88, 0x140000
	s_addc_u32 s1, s89, 0
	v_writelane_b32 v254, s0, 30
	v_and_b32_e32 v1, 16, v134
	v_and_b32_e32 v3, 8, v134
	v_writelane_b32 v254, s1, 31
	s_movk_i32 s0, 0x4f
	v_cmp_lt_u32_e64 s[0:1], s0, v134
	v_and_b32_e32 v17, 4, v134
	v_and_b32_e32 v18, 3, v134
	v_writelane_b32 v254, s0, 32
	v_lshlrev_b32_e32 v2, 2, v19
	v_add_u32_e32 v4, 0x1400, v57
	v_writelane_b32 v254, s1, 33
	s_movk_i32 s0, 0x5f
	v_cmp_lt_u32_e64 s[0:1], s0, v134
	v_add_u32_e32 v20, 0x2800, v57
	v_add_u32_e32 v21, 0x3c00, v57
	v_writelane_b32 v254, s0, 34
	v_add_u32_e32 v22, 0x5000, v57
	v_add_u32_e32 v23, 0x6400, v57
	v_writelane_b32 v254, s1, 35
	s_movk_i32 s0, 0x6f
	v_cmp_lt_u32_e64 s[0:1], s0, v134
	v_add_u32_e32 v24, 0x7800, v57
	v_add_u32_e32 v25, 0x8c00, v57
	v_writelane_b32 v254, s0, 36
	v_add_u32_e32 v26, 0xa000, v57
	v_add_u32_e32 v27, 0xb400, v57
	v_writelane_b32 v254, s1, 37
	s_movk_i32 s0, 0x7f
	v_cmp_lt_u32_e64 s[0:1], s0, v134
	v_mul_u32_u24_e32 v28, 0x50, v0
	v_lshlrev_b32_e32 v58, 2, v0
	v_writelane_b32 v254, s0, 38
	v_add_u32_e32 v0, 0xc800, v57
	v_mov_b32_e32 v15, v5
	v_writelane_b32 v254, s1, 39
	s_movk_i32 s0, 0x8f
	v_cmp_lt_u32_e64 s[0:1], s0, v134
	v_add_u32_e32 v29, 0xdc00, v57
	v_add_u32_e32 v30, 0xf000, v57
	v_writelane_b32 v254, s0, 40
	v_add_u32_e32 v31, 0x10400, v57
	v_add_u32_e32 v32, 0x11800, v57
	v_writelane_b32 v254, s1, 41
	s_movk_i32 s0, 0x9f
	v_cmp_lt_u32_e64 s[0:1], s0, v134
	v_mbcnt_lo_u32_b32 v33, -1, 0
	s_mov_b32 s67, 0
	v_writelane_b32 v254, s0, 42
	v_add_u32_e32 v49, s4, v14
	v_add_u32_e32 v51, s4, v132
	v_writelane_b32 v254, s1, 43
	s_movk_i32 s0, 0xaf
	v_cmp_lt_u32_e64 s[16:17], s0, v134
	s_movk_i32 s0, 0xbf
	v_cmp_lt_u32_e64 s[18:19], s0, v134
	s_movk_i32 s0, 0xcf
	v_cmp_lt_u32_e64 s[20:21], s0, v134
	s_movk_i32 s0, 0xdf
	v_cmp_lt_u32_e64 s[22:23], s0, v134
	s_movk_i32 s0, 0xef
	v_lshrrev_b32_e32 v8, 2, v132
	v_lshl_add_u64 v[10:11], s[70:71], 0, v[132:133]
	v_or_b32_e32 v56, 0xffffef00, v52
	v_cmp_lt_u32_e64 s[24:25], s0, v134
	v_lshl_add_u64 v[14:15], s[60:61], 0, v[14:15]
	s_mov_b32 s49, 0xf800000
	s_mov_b32 s70, 0xbfb8aa3b
	s_mov_b32 s71, 0xb2a5705f
	s_mov_b32 s50, 0x42ce8ed0
	v_lshlrev_b32_e32 v59, 2, v132
	s_mov_b32 s94, 0xc2b17218
	v_mov_b32_e32 v60, 0x358637bd
	s_mov_b32 s95, 0x7f800000
	v_mov_b32_e32 v61, 0x260
	s_mov_b32 s4, 0x3f2aaaab
	v_mov_b32_e32 v62, 0x3ecc95a3
	s_mov_b32 s5, 0x3f317218
	s_mov_b32 s6, 0x33800000
	v_mov_b32_e32 v63, 0x7f800000
	s_mov_b32 s7, 0xc400000
	v_lshlrev_b32_e32 v16, 2, v2
	v_mbcnt_hi_u32_b32 v64, -1, v33
	v_add_u32_e32 v65, s51, v4
	v_add_u32_e32 v66, s51, v20
	v_add_u32_e32 v67, s51, v21
	v_add_u32_e32 v68, s51, v22
	v_add_u32_e32 v69, s51, v23
	v_add_u32_e32 v70, s51, v24
	v_add_u32_e32 v71, s51, v25
	v_add_u32_e32 v72, s51, v26
	v_add_u32_e32 v73, s51, v27
	v_add_u32_e32 v74, s51, v0
	v_add_u32_e32 v75, s51, v29
	v_add_u32_e32 v76, s51, v30
	v_add_u32_e32 v77, s51, v31
	v_add_u32_e32 v78, s51, v32
	v_add_u32_e32 v79, s51, v28
	s_mov_b32 s33, s44
	v_cmp_gt_u32_e64 s[26:27], 32, v132
	v_cmp_eq_u32_e64 s[28:29], 0, v1
	v_cmp_eq_u32_e64 s[30:31], 0, v3
	v_cmp_eq_u32_e64 s[34:35], 0, v17
	v_cmp_eq_u32_e64 s[36:37], 0, v18
	v_cmp_eq_u32_e64 s[38:39], 15, v19
	v_cmp_gt_u32_e64 s[40:41], 16, v134
	v_cmp_lt_u32_e64 s[42:43], 31, v134
	v_cmp_lt_u32_e64 s[8:9], 47, v134
	v_cmp_lt_u32_e64 s[46:47], 63, v134
	v_add_u32_e32 v252, s51, v57
	ds_read_b128 v[160:163], v252
	ds_read_b128 v[164:167], v252 offset:16
	ds_read_b128 v[168:171], v252 offset:32
	ds_read_b128 v[172:175], v252 offset:48
	ds_read_b128 v[176:179], v65
	ds_read_b128 v[180:183], v65 offset:16
	ds_read_b128 v[184:187], v65 offset:32
	ds_read_b128 v[188:191], v65 offset:48
	ds_read_b128 v[192:195], v66
	ds_read_b128 v[196:199], v66 offset:16
	ds_read_b128 v[200:203], v66 offset:32
	ds_read_b128 v[204:207], v66 offset:48
	s_waitcnt lgkmcnt(0)
	ds_read_b128 v[208:211], v67
	ds_read_b128 v[212:215], v67 offset:16
	ds_read_b128 v[216:219], v67 offset:32
	ds_read_b128 v[220:223], v67 offset:48
	ds_read_b128 v[224:227], v68
	ds_read_b128 v[228:231], v68 offset:16
	ds_read_b128 v[232:235], v68 offset:32
	ds_read_b128 v[236:239], v68 offset:48
	ds_read_b128 v[240:243], v69
	ds_read_b128 v[244:247], v69 offset:16
	ds_read_b128 v[248:251], v69 offset:32
	s_waitcnt lgkmcnt(0)
	s_branch .LBB0_28

; __device__ __forceinline__ void p0_phase(const Args& a, LAS unsigned char* lds, int tid, int lane, int wave) {
;     ...
;             for (int i4 = 0; i4 < 2; ++i4) {
;                 float xa[4][16];
; #pragma unroll
;                 for (int u = 0; u < 4; ++u) { const int row = c * 64 + wave * 8 + i4 * 4 + u; const float* xrow = row < MP ? a.in[0] + (size_t)row * D : a.in[1] + (size_t)(row - MP) * D;
; #pragma unroll
;                     for (int j = 0; j < 16; ++j) xa[u][j] = xrow[lane + 64 * j]; }
; #pragma unroll
;                 for (int u = 0; u < 4; ++u) {
;                 const int rl = wave * 8 + i4 * 4 + u, row = c * 64 + rl;
;                 float ss = 0.f;
; #pragma unroll
;                 for (int j = 0; j < 16; ++j) ss += xa[u][j] * xa[u][j];
;                 const float rstd = 1.0f / sqrtf(wave_sum(ss) * (1.f / D) + EPS);
.LBB0_33:
	s_or_b32 s11, s10, s66
	s_add_i32 s0, s11, 0xffffc000
	s_ashr_i32 s1, s11, 31
	s_cmpk_lt_i32 s11, 0x4000
	s_cselect_b32 s1, s1, 0
	s_cselect_b32 s0, s11, s0
	s_cselect_b32 s12, s53, s55
	s_cselect_b32 s13, s52, s54
	s_lshl_b64 s[0:1], s[0:1], 12
	s_add_u32 s0, s13, s0
	s_addc_u32 s1, s12, s1
	global_load_dword v126, v59, s[0:1] offset:256
	global_load_dword v147, v59, s[0:1] offset:512
	global_load_dword v146, v59, s[0:1] offset:768
	global_load_dword v145, v59, s[0:1] offset:1024
	global_load_dword v144, v59, s[0:1] offset:1280
	global_load_dword v143, v59, s[0:1] offset:1536
	global_load_dword v142, v59, s[0:1] offset:1792
	global_load_dword v0, v59, s[0:1]
	global_load_dword v141, v59, s[0:1] offset:2048
	global_load_dword v127, v59, s[0:1] offset:2304
	global_load_dword v120, v59, s[0:1] offset:2560
	global_load_dword v119, v59, s[0:1] offset:2816
	global_load_dword v118, v59, s[0:1] offset:3072
	global_load_dword v117, v59, s[0:1] offset:3328
	global_load_dword v116, v59, s[0:1] offset:3584
	global_load_dword v33, v58, s[0:1]
	s_or_b32 s0, s11, 1
	s_add_i32 s12, s11, 0xffffc001
	s_ashr_i32 s1, s0, 31
	s_cmpk_lt_i32 s0, 0x4000
	s_cselect_b32 s1, s1, 0
	s_cselect_b32 s0, s0, s12
	s_cselect_b32 s12, s53, s55
	s_cselect_b32 s13, s52, s54
	s_lshl_b64 s[0:1], s[0:1], 12
	s_add_u32 vcc_lo, s13, s0
	s_addc_u32 vcc_hi, s12, s1
	s_or_b32 s0, s11, 2
	s_add_i32 s12, s11, 0xffffc002
	s_ashr_i32 s1, s0, 31
	s_cmpk_lt_i32 s0, 0x4000
	s_cselect_b32 s1, s1, 0
	s_cselect_b32 s0, s0, s12
	s_cselect_b32 s12, s53, s55
	s_cselect_b32 s13, s52, s54
	s_lshl_b64 s[0:1], s[0:1], 12
	s_add_u32 s0, s13, s0
	s_addc_u32 s1, s12, s1
	s_or_b32 s12, s11, 3
	s_addk_i32 s11, 0xc003
	s_ashr_i32 s13, s12, 31
	s_cmpk_lt_i32 s12, 0x4000
	s_cselect_b32 s93, s13, 0
	s_cselect_b32 s92, s12, s11
	s_cselect_b32 s11, s53, s55
	s_cselect_b32 s12, s52, s54
	s_lshl_b64 s[92:93], s[92:93], 12
	s_add_u32 s92, s12, s92
	global_load_dword v111, v59, vcc
	s_addc_u32 s93, s11, s93
	global_load_dword v100, v58, vcc
	global_load_dword v84, v58, s[0:1]
	global_load_dword v20, v58, s[92:93]
	global_load_dword v115, v59, vcc offset:256
	global_load_dword v114, v59, vcc offset:512
	global_load_dword v113, v59, vcc offset:768
	global_load_dword v112, v59, vcc offset:1024
	global_load_dword v110, v59, vcc offset:1280
	global_load_dword v109, v59, vcc offset:1536
	global_load_dword v108, v59, vcc offset:1792
	global_load_dword v107, v59, vcc offset:2048
	global_load_dword v106, v59, vcc offset:2304
	global_load_dword v105, v59, vcc offset:2560
	global_load_dword v104, v59, vcc offset:2816
	global_load_dword v103, v59, vcc offset:3072
	global_load_dword v102, v59, vcc offset:3328
	global_load_dword v101, v59, vcc offset:3584
	global_load_dword v99, v59, s[0:1]
	global_load_dword v98, v59, s[0:1] offset:256
	global_load_dword v97, v59, s[0:1] offset:512
	global_load_dword v96, v59, s[0:1] offset:768
	global_load_dword v95, v59, s[0:1] offset:1024
	global_load_dword v94, v59, s[0:1] offset:1280
	global_load_dword v93, v59, s[0:1] offset:1536
	global_load_dword v92, v59, s[0:1] offset:1792
	global_load_dword v91, v59, s[0:1] offset:2048
	global_load_dword v90, v59, s[0:1] offset:2304
	global_load_dword v89, v59, s[0:1] offset:2560
	global_load_dword v88, v59, s[0:1] offset:2816
	global_load_dword v87, v59, s[0:1] offset:3072
	global_load_dword v86, v59, s[0:1] offset:3328
	global_load_dword v85, v59, s[0:1] offset:3584
	global_load_dword v82, v59, s[92:93]
	global_load_dword v81, v59, s[92:93] offset:256
	global_load_dword v80, v59, s[92:93] offset:512
	s_or_b32 s10, s10, s48
	s_waitcnt vmcnt(51)
	v_mul_f32_e32 v1, v126, v126
	s_waitcnt vmcnt(44)
	v_fmac_f32_e32 v1, v0, v0
	v_fmac_f32_e32 v1, v147, v147
	v_fmac_f32_e32 v1, v146, v146
	v_fmac_f32_e32 v1, v145, v145
	v_fmac_f32_e32 v1, v144, v144
	v_fmac_f32_e32 v1, v143, v143
	v_fmac_f32_e32 v1, v142, v142
	s_waitcnt vmcnt(43)
	v_fmac_f32_e32 v1, v141, v141
	s_waitcnt vmcnt(42)
	v_fmac_f32_e32 v1, v127, v127
	s_waitcnt vmcnt(41)
	v_fmac_f32_e32 v1, v120, v120
	s_waitcnt vmcnt(40)
	v_fmac_f32_e32 v1, v119, v119
	s_waitcnt vmcnt(39)
	v_fmac_f32_e32 v1, v118, v118
	s_waitcnt vmcnt(38)
	v_fmac_f32_e32 v1, v117, v117
	s_waitcnt vmcnt(37)
	v_fmac_f32_e32 v1, v116, v116
	s_waitcnt vmcnt(36)
	v_fmac_f32_e32 v1, v33, v33
	s_waitcnt lgkmcnt(0)
	ds_bpermute_b32 v21, v2, v1
	s_waitcnt lgkmcnt(0)
	v_add_f32_e32 v1, v1, v21
	ds_bpermute_b32 v21, v3, v1
	s_waitcnt lgkmcnt(0)
	v_add_f32_e32 v1, v1, v21
	ds_bpermute_b32 v21, v4, v1
	s_waitcnt lgkmcnt(0)
	v_add_f32_e32 v1, v1, v21
	ds_bpermute_b32 v21, v17, v1
	s_waitcnt lgkmcnt(0)
	v_add_f32_e32 v1, v1, v21
	ds_bpermute_b32 v21, v18, v1
	s_waitcnt lgkmcnt(0)
	v_add_f32_e32 v1, v1, v21
	ds_bpermute_b32 v21, v19, v1
	s_waitcnt lgkmcnt(0)
; #define LAS __attribute__((address_space(3)))
; __device__ __forceinline__ unsigned cvt_pk_bf16(float lo, float hi) { unsigned r; asm volatile("v_cvt_pk_bf16_f32 %0, %1, %2" : "=v"(r) : "v"(lo), "v"(hi)); return r; }
; __device__ __forceinline__ void p0_phase(const Args& a, LAS unsigned char* lds, int tid, int lane, int wave) {
;     ...
;                 const float rstd = 1.0f / sqrtf(wave_sum(ss) * (1.f / D) + EPS);
;                 float f[16];
; #pragma unroll
;                 for (int h = 0; h < 16; ++h) f[h] = 0.f;
; #pragma unroll
;                 for (int j = 0; j < 16; ++j) { const float xn = xa[u][j] * rstd * gm[j];
;                     XN[(size_t)row * D + lane + 64 * j] = (bf16_t)(cvt_pk_bf16(xn, 0.f) & 0xffffu);
;                     const LAS f32x4* wp = (const LAS f32x4*)(wfl + (lane + 64 * j) * 16);
; #pragma unroll
;                     for (int q = 0; q < 4; ++q) { const f32x4 w = wp[q]; f[4 * q + 0] += xn * w[0]; f[4 * q + 1] += xn * w[1]; f[4 * q + 2] += xn * w[2]; f[4 * q + 3] += xn * w[3]; } }
	v_add_f32_e32 v1, v1, v21
	v_fmamk_f32 v1, v1, 0x3a800000, v60
	v_mul_f32_e32 v21, 0x4f800000, v1
	v_cmp_gt_f32_e32 vcc, s49, v1
	s_nop 1
	v_cndmask_b32_e32 v1, v1, v21, vcc
	v_sqrt_f32_e32 v21, v1
	s_nop 0
	v_add_u32_e32 v22, -1, v21
	v_add_u32_e32 v23, 1, v21
	v_fma_f32 v24, -v22, v21, v1
	v_fma_f32 v25, -v23, v21, v1
	v_cmp_ge_f32_e64 s[0:1], 0, v24
	s_nop 1
	v_cndmask_b32_e64 v21, v21, v22, s[0:1]
	v_cmp_lt_f32_e64 s[0:1], 0, v25
	global_load_dword v32, v59, s[92:93] offset:768
	global_load_dword v31, v59, s[92:93] offset:1024
	global_load_dword v30, v59, s[92:93] offset:1280
	global_load_dword v29, v59, s[92:93] offset:1536
	global_load_dword v28, v59, s[92:93] offset:1792
	global_load_dword v27, v59, s[92:93] offset:2048
	global_load_dword v26, v59, s[92:93] offset:2304
	global_load_dword v25, v59, s[92:93] offset:2560
	v_cndmask_b32_e64 v21, v21, v23, s[0:1]
	v_mul_f32_e32 v22, 0x37800000, v21
	v_cndmask_b32_e32 v21, v21, v22, vcc
	v_cmp_class_f32_e32 vcc, v1, v61
	s_nop 1
	v_cndmask_b32_e32 v1, v21, v1, vcc
	v_div_scale_f32 v21, s[0:1], v1, v1, 1.0
	v_rcp_f32_e32 v22, v21
	v_div_scale_f32 v23, vcc, 1.0, v1, 1.0
	s_add_i32 s0, s10, s45
	v_fma_f32 v24, -v21, v22, 1.0
	v_fmac_f32_e32 v22, v24, v22
	v_mul_f32_e32 v24, v23, v22
	v_fma_f32 v83, -v21, v24, v23
	v_fmac_f32_e32 v24, v83, v22
	v_fma_f32 v21, -v21, v24, v23
	v_div_fmas_f32 v21, v21, v22, v24
	v_div_fixup_f32 v139, v21, v1, 1.0
	v_mul_f32_e32 v0, v0, v139
	v_add_u32_e32 v83, s51, v57
	v_mul_f32_e32 v156, v9, v0
	global_load_dword v24, v59, s[92:93] offset:2816
	global_load_dword v23, v59, s[92:93] offset:3072
	global_load_dword v22, v59, s[92:93] offset:3328
	global_load_dword v21, v59, s[92:93] offset:3584
	v_cvt_pk_bf16_f32 v131, v156, v5
	s_ashr_i32 s1, s0, 31
	s_lshl_b64 s[92:93], s[0:1], 11
	s_waitcnt lgkmcnt(0)
	v_fma_f32 v135, v160, v156, 0
	v_fma_f32 v130, v161, v156, 0
	v_fma_f32 v129, v162, v156, 0
	s_waitcnt lgkmcnt(0)
	v_fma_f32 v122, v164, v156, 0
	v_fma_f32 v124, v165, v156, 0
	v_fma_f32 v123, v166, v156, 0
	v_fma_f32 v121, v167, v156, 0
	v_lshl_add_u64 v[0:1], v[6:7], 0, s[92:93]
	v_mul_f32_e32 v126, v126, v139
	s_waitcnt lgkmcnt(0)
	v_fma_f32 v140, v168, v156, 0
	v_fma_f32 v138, v169, v156, 0
	v_fma_f32 v137, v170, v156, 0
	v_fma_f32 v133, v171, v156, 0
	s_waitcnt lgkmcnt(0)
	v_fma_f32 v128, v156, v172, 0
	global_store_short v[0:1], v131, off
	v_mul_f32_e32 v157, v34, v126
	v_cvt_pk_bf16_f32 v158, v157, v5
	v_fma_f32 v136, v156, v173, 0
	v_fma_f32 v131, v156, v174, 0
	v_fma_f32 v126, v156, v175, 0
	v_fma_f32 v125, v163, v156, 0
	s_waitcnt lgkmcnt(0)
	v_fmac_f32_e32 v135, v157, v176
	v_fmac_f32_e32 v130, v157, v177
	v_fmac_f32_e32 v129, v157, v178
	v_fmac_f32_e32 v125, v157, v179
	s_waitcnt lgkmcnt(0)
	v_fmac_f32_e32 v122, v157, v180
	v_fmac_f32_e32 v124, v157, v181
	v_fmac_f32_e32 v123, v157, v182
	v_fmac_f32_e32 v121, v157, v183
	v_mul_f32_e32 v147, v147, v139
	s_waitcnt lgkmcnt(0)
	v_fmac_f32_e32 v140, v157, v184
	v_fmac_f32_e32 v138, v157, v185
	v_fmac_f32_e32 v137, v157, v186
	v_fmac_f32_e32 v133, v157, v187
	s_waitcnt lgkmcnt(0)
	v_fmac_f32_e32 v128, v157, v188
	global_store_short v[0:1], v158, off offset:128
	v_mul_f32_e32 v147, v35, v147
	v_cvt_pk_bf16_f32 v156, v147, v5
	v_fmac_f32_e32 v136, v157, v189
	v_fmac_f32_e32 v131, v157, v190
	v_fmac_f32_e32 v126, v157, v191
	s_waitcnt lgkmcnt(0)
	v_fmac_f32_e32 v135, v147, v192
	v_fmac_f32_e32 v130, v147, v193
	v_fmac_f32_e32 v129, v147, v194
	v_fmac_f32_e32 v125, v147, v195
	s_waitcnt lgkmcnt(0)
	v_fmac_f32_e32 v122, v147, v196
	v_fmac_f32_e32 v124, v147, v197
	v_fmac_f32_e32 v123, v147, v198
	v_fmac_f32_e32 v121, v147, v199
	v_mul_f32_e32 v146, v146, v139
	s_waitcnt lgkmcnt(0)
	v_fmac_f32_e32 v140, v147, v200
	v_fmac_f32_e32 v138, v147, v201
	v_fmac_f32_e32 v137, v147, v202
	v_fmac_f32_e32 v133, v147, v203
	s_waitcnt lgkmcnt(0)
	v_fmac_f32_e32 v128, v147, v204
	global_store_short v[0:1], v156, off offset:256
	v_mul_f32_e32 v156, v36, v146
	v_cvt_pk_bf16_f32 v157, v156, v5
	v_fmac_f32_e32 v136, v147, v205
	v_fmac_f32_e32 v131, v147, v206
	v_fmac_f32_e32 v126, v147, v207
	s_waitcnt lgkmcnt(0)
	v_fmac_f32_e32 v135, v156, v208
	v_fmac_f32_e32 v130, v156, v209
	v_mul_f32_e32 v145, v145, v139
	s_waitcnt lgkmcnt(0)
	v_fmac_f32_e32 v122, v156, v212
	v_fmac_f32_e32 v124, v156, v213
	v_fmac_f32_e32 v123, v156, v214
	v_fmac_f32_e32 v121, v156, v215
	v_fmac_f32_e32 v129, v156, v210
	s_waitcnt lgkmcnt(0)
	v_fmac_f32_e32 v140, v156, v216
	v_fmac_f32_e32 v138, v156, v217
	v_fmac_f32_e32 v137, v156, v218
	v_fmac_f32_e32 v133, v156, v219
	s_waitcnt lgkmcnt(0)
	v_fmac_f32_e32 v128, v156, v220
	global_store_short v[0:1], v157, off offset:384
	v_mul_f32_e32 v145, v37, v145
	v_cvt_pk_bf16_f32 v154, v145, v5
	v_fmac_f32_e32 v136, v156, v221
	v_fmac_f32_e32 v131, v156, v222
	v_fmac_f32_e32 v126, v156, v223
	v_fmac_f32_e32 v125, v156, v211
	s_waitcnt lgkmcnt(0)
	v_fmac_f32_e32 v135, v145, v224
	v_fmac_f32_e32 v130, v145, v225
	v_fmac_f32_e32 v129, v145, v226
	v_fmac_f32_e32 v125, v145, v227
	s_waitcnt lgkmcnt(0)
	v_fmac_f32_e32 v122, v145, v228
	v_fmac_f32_e32 v124, v145, v229
	v_fmac_f32_e32 v123, v145, v230
	v_fmac_f32_e32 v121, v145, v231
	v_mul_f32_e32 v144, v144, v139
	s_waitcnt lgkmcnt(0)
	v_fmac_f32_e32 v140, v145, v232
	v_fmac_f32_e32 v138, v145, v233
	v_fmac_f32_e32 v137, v145, v234
	v_fmac_f32_e32 v133, v145, v235
	s_waitcnt lgkmcnt(0)
	v_fmac_f32_e32 v128, v145, v236
	global_store_short v[0:1], v154, off offset:512
	v_mul_f32_e32 v154, v38, v144
	v_cvt_pk_bf16_f32 v155, v154, v5
	v_fmac_f32_e32 v136, v145, v237
	v_fmac_f32_e32 v131, v145, v238
	v_fmac_f32_e32 v126, v145, v239
	s_waitcnt lgkmcnt(0)
; #define LAS __attribute__((address_space(3)))
; __device__ __forceinline__ unsigned cvt_pk_bf16(float lo, float hi) { unsigned r; asm volatile("v_cvt_pk_bf16_f32 %0, %1, %2" : "=v"(r) : "v"(lo), "v"(hi)); return r; }
; __device__ __forceinline__ void p0_phase(const Args& a, LAS unsigned char* lds, int tid, int lane, int wave) {
;     ...
;                 for (int j = 0; j < 16; ++j) { const float xn = xa[u][j] * rstd * gm[j];
;                     XN[(size_t)row * D + lane + 64 * j] = (bf16_t)(cvt_pk_bf16(xn, 0.f) & 0xffffu);
;                     const LAS f32x4* wp = (const LAS f32x4*)(wfl + (lane + 64 * j) * 16);
; #pragma unroll
;                     for (int q = 0; q < 4; ++q) { const f32x4 w = wp[q]; f[4 * q + 0] += xn * w[0]; f[4 * q + 1] += xn * w[1]; f[4 * q + 2] += xn * w[2]; f[4 * q + 3] += xn * w[3]; } }
	v_fmac_f32_e32 v135, v154, v240
	v_fmac_f32_e32 v130, v154, v241
	v_mul_f32_e32 v143, v143, v139
	s_waitcnt lgkmcnt(0)
	v_fmac_f32_e32 v122, v154, v244
	v_fmac_f32_e32 v124, v154, v245
	v_fmac_f32_e32 v123, v154, v246
	v_fmac_f32_e32 v121, v154, v247
	ds_read_b128 v[144:147], v69 offset:48
	v_fmac_f32_e32 v129, v154, v242
	s_waitcnt lgkmcnt(1)
	v_fmac_f32_e32 v140, v154, v248
	v_fmac_f32_e32 v138, v154, v249
	v_fmac_f32_e32 v137, v154, v250
	v_fmac_f32_e32 v133, v154, v251
	s_waitcnt lgkmcnt(0)
	v_fmac_f32_e32 v128, v154, v144
	global_store_short v[0:1], v155, off offset:640
	v_mul_f32_e32 v143, v39, v143
	v_cvt_pk_bf16_f32 v152, v143, v5
	ds_read_b128 v[148:151], v70
	v_fmac_f32_e32 v136, v154, v145
	v_fmac_f32_e32 v131, v154, v146
	v_fmac_f32_e32 v126, v154, v147
	ds_read_b128 v[144:147], v70 offset:16
	v_fmac_f32_e32 v125, v154, v243
	s_waitcnt lgkmcnt(1)
	v_fmac_f32_e32 v135, v143, v148
	v_fmac_f32_e32 v130, v143, v149
	v_fmac_f32_e32 v129, v143, v150
	v_fmac_f32_e32 v125, v143, v151
	s_waitcnt lgkmcnt(0)
	v_fmac_f32_e32 v122, v143, v144
	ds_read_b128 v[148:151], v70 offset:32
	v_fmac_f32_e32 v124, v143, v145
	v_fmac_f32_e32 v123, v143, v146
	v_fmac_f32_e32 v121, v143, v147
	ds_read_b128 v[144:147], v70 offset:48
	v_mul_f32_e32 v142, v142, v139
	s_waitcnt lgkmcnt(1)
	v_fmac_f32_e32 v140, v143, v148
	v_fmac_f32_e32 v138, v143, v149
	v_fmac_f32_e32 v137, v143, v150
	v_fmac_f32_e32 v133, v143, v151
	s_waitcnt lgkmcnt(0)
	v_fmac_f32_e32 v128, v143, v144
	global_store_short v[0:1], v152, off offset:768
	v_mul_f32_e32 v152, v40, v142
	v_cvt_pk_bf16_f32 v153, v152, v5
	ds_read_b128 v[148:151], v71
	v_fmac_f32_e32 v136, v143, v145
	v_fmac_f32_e32 v131, v143, v146
	v_fmac_f32_e32 v126, v143, v147
	ds_read_b128 v[142:145], v71 offset:16
	s_waitcnt lgkmcnt(1)
	v_fmac_f32_e32 v135, v152, v148
	v_fmac_f32_e32 v130, v152, v149
	ds_read_b128 v[146:149], v71 offset:32
	v_mul_f32_e32 v141, v141, v139
	s_waitcnt lgkmcnt(1)
	v_fmac_f32_e32 v122, v152, v142
	v_fmac_f32_e32 v124, v152, v143
	v_fmac_f32_e32 v123, v152, v144
	v_fmac_f32_e32 v121, v152, v145
	ds_read_b128 v[142:145], v71 offset:48
	v_fmac_f32_e32 v129, v152, v150
	s_waitcnt lgkmcnt(1)
	v_fmac_f32_e32 v140, v152, v146
	v_fmac_f32_e32 v138, v152, v147
	v_fmac_f32_e32 v137, v152, v148
	v_fmac_f32_e32 v133, v152, v149
	s_waitcnt lgkmcnt(0)
	v_fmac_f32_e32 v128, v152, v142
	global_store_short v[0:1], v153, off offset:896
	v_mul_f32_e32 v141, v41, v141
	v_cvt_pk_bf16_f32 v150, v141, v5
	ds_read_b128 v[146:149], v72
	v_fmac_f32_e32 v136, v152, v143
	v_fmac_f32_e32 v131, v152, v144
	v_fmac_f32_e32 v126, v152, v145
	ds_read_b128 v[142:145], v72 offset:16
	v_fmac_f32_e32 v125, v152, v151
	s_waitcnt lgkmcnt(1)
	v_fmac_f32_e32 v135, v141, v146
	v_fmac_f32_e32 v130, v141, v147
	v_fmac_f32_e32 v129, v141, v148
	v_fmac_f32_e32 v125, v141, v149
	s_waitcnt lgkmcnt(0)
	v_fmac_f32_e32 v122, v141, v142
	ds_read_b128 v[146:149], v72 offset:32
	v_fmac_f32_e32 v124, v141, v143
	v_fmac_f32_e32 v123, v141, v144
	v_fmac_f32_e32 v121, v141, v145
	ds_read_b128 v[142:145], v72 offset:48
	v_mul_f32_e32 v127, v127, v139
	s_waitcnt lgkmcnt(1)
	v_fmac_f32_e32 v140, v141, v146
	v_fmac_f32_e32 v138, v141, v147
	v_fmac_f32_e32 v137, v141, v148
	v_fmac_f32_e32 v133, v141, v149
	s_waitcnt lgkmcnt(0)
	v_fmac_f32_e32 v128, v141, v142
	global_store_short v[0:1], v150, off offset:1024
	v_mul_f32_e32 v127, v42, v127
	v_cvt_pk_bf16_f32 v150, v127, v5
	ds_read_b128 v[146:149], v73
	v_fmac_f32_e32 v136, v141, v143
	v_fmac_f32_e32 v131, v141, v144
	v_fmac_f32_e32 v126, v141, v145
	ds_read_b128 v[142:145], v73 offset:16
	s_waitcnt lgkmcnt(1)
	v_fmac_f32_e32 v135, v127, v146
	v_fmac_f32_e32 v130, v127, v147
	v_fmac_f32_e32 v129, v127, v148
	v_fmac_f32_e32 v125, v127, v149
	s_waitcnt lgkmcnt(0)
	v_fmac_f32_e32 v122, v127, v142
	ds_read_b128 v[146:149], v73 offset:32
	v_fmac_f32_e32 v124, v127, v143
	v_fmac_f32_e32 v123, v127, v144
	v_fmac_f32_e32 v121, v127, v145
	ds_read_b128 v[142:145], v73 offset:48
	v_mul_f32_e32 v120, v120, v139
	s_waitcnt lgkmcnt(1)
	v_fmac_f32_e32 v140, v127, v146
	v_fmac_f32_e32 v138, v127, v147
	v_fmac_f32_e32 v137, v127, v148
	v_fmac_f32_e32 v133, v127, v149
	s_waitcnt lgkmcnt(0)
	v_fmac_f32_e32 v128, v127, v142
	global_store_short v[0:1], v150, off offset:1152
	v_mul_f32_e32 v120, v43, v120
	v_cvt_pk_bf16_f32 v141, v120, v5
	ds_read_b128 v[146:149], v74
	v_fmac_f32_e32 v136, v127, v143
	v_fmac_f32_e32 v131, v127, v144
	v_fmac_f32_e32 v126, v127, v145
	ds_read_b128 v[142:145], v74 offset:16
	s_waitcnt lgkmcnt(1)
	v_fmac_f32_e32 v135, v120, v146
	v_fmac_f32_e32 v130, v120, v147
	v_fmac_f32_e32 v129, v120, v148
	v_fmac_f32_e32 v125, v120, v149
	s_waitcnt lgkmcnt(0)
	v_fmac_f32_e32 v122, v120, v142
	ds_read_b128 v[146:149], v74 offset:32
	v_fmac_f32_e32 v124, v120, v143
	v_fmac_f32_e32 v123, v120, v144
	v_fmac_f32_e32 v121, v120, v145
	ds_read_b128 v[142:145], v74 offset:48
	v_mul_f32_e32 v119, v119, v139
	s_waitcnt lgkmcnt(1)
	v_fmac_f32_e32 v140, v120, v146
	v_fmac_f32_e32 v138, v120, v147
	v_fmac_f32_e32 v137, v120, v148
	v_fmac_f32_e32 v133, v120, v149
	s_waitcnt lgkmcnt(0)
	v_fmac_f32_e32 v128, v120, v142
	global_store_short v[0:1], v141, off offset:1280
	v_mul_f32_e32 v119, v44, v119
	v_cvt_pk_bf16_f32 v127, v119, v5
	ds_read_b128 v[146:149], v75
	v_fmac_f32_e32 v136, v120, v143
	v_fmac_f32_e32 v131, v120, v144
	v_fmac_f32_e32 v126, v120, v145
	ds_read_b128 v[142:145], v75 offset:16
	s_waitcnt lgkmcnt(1)
	v_fmac_f32_e32 v135, v119, v146
	v_fmac_f32_e32 v130, v119, v147
	v_fmac_f32_e32 v129, v119, v148
	v_fmac_f32_e32 v125, v119, v149
	s_waitcnt lgkmcnt(0)
; #define LAS __attribute__((address_space(3)))
; __device__ __forceinline__ unsigned cvt_pk_bf16(float lo, float hi) { unsigned r; asm volatile("v_cvt_pk_bf16_f32 %0, %1, %2" : "=v"(r) : "v"(lo), "v"(hi)); return r; }
; __device__ __forceinline__ void p0_phase(const Args& a, LAS unsigned char* lds, int tid, int lane, int wave) {
;     ...
;                 for (int j = 0; j < 16; ++j) { const float xn = xa[u][j] * rstd * gm[j];
;                     XN[(size_t)row * D + lane + 64 * j] = (bf16_t)(cvt_pk_bf16(xn, 0.f) & 0xffffu);
;                     const LAS f32x4* wp = (const LAS f32x4*)(wfl + (lane + 64 * j) * 16);
; #pragma unroll
;                     for (int q = 0; q < 4; ++q) { const f32x4 w = wp[q]; f[4 * q + 0] += xn * w[0]; f[4 * q + 1] += xn * w[1]; f[4 * q + 2] += xn * w[2]; f[4 * q + 3] += xn * w[3]; } }
;                 { const bool b5 = lane & 32;
; #pragma unroll
;                   for (int k = 0; k < 8; ++k) { const float send = b5 ? f[k] : f[k + 8], keep = b5 ? f[k + 8] : f[k]; f[k] = keep + __shfl_xor(send, 32); }
;                   const bool b4 = lane & 16;
; #pragma unroll
;                   for (int k = 0; k < 4; ++k) { const float send = b4 ? f[k] : f[k + 4], keep = b4 ? f[k + 4] : f[k]; f[k] = keep + __shfl_xor(send, 16); }
;                   const bool b3 = lane & 8;
; #pragma unroll
;                   for (int k = 0; k < 2; ++k) { const float send = b3 ? f[k] : f[k + 2], keep = b3 ? f[k + 2] : f[k]; f[k] = keep + __shfl_xor(send, 8); }
	v_fmac_f32_e32 v122, v119, v142
	ds_read_b128 v[146:149], v75 offset:32
	v_fmac_f32_e32 v124, v119, v143
	v_fmac_f32_e32 v123, v119, v144
	v_fmac_f32_e32 v121, v119, v145
	ds_read_b128 v[142:145], v75 offset:48
	v_mul_f32_e32 v118, v118, v139
	s_waitcnt lgkmcnt(1)
	v_fmac_f32_e32 v140, v119, v146
	v_fmac_f32_e32 v138, v119, v147
	v_fmac_f32_e32 v137, v119, v148
	v_fmac_f32_e32 v133, v119, v149
	s_waitcnt lgkmcnt(0)
	v_fmac_f32_e32 v128, v119, v142
	global_store_short v[0:1], v127, off offset:1408
	v_mul_f32_e32 v118, v45, v118
	v_cvt_pk_bf16_f32 v120, v118, v5
	ds_read_b128 v[146:149], v76
	v_fmac_f32_e32 v136, v119, v143
	v_fmac_f32_e32 v131, v119, v144
	v_fmac_f32_e32 v126, v119, v145
	ds_read_b128 v[142:145], v76 offset:16
	s_waitcnt lgkmcnt(1)
	v_fmac_f32_e32 v135, v118, v146
	v_fmac_f32_e32 v130, v118, v147
	v_fmac_f32_e32 v129, v118, v148
	v_fmac_f32_e32 v125, v118, v149
	s_waitcnt lgkmcnt(0)
	v_fmac_f32_e32 v122, v118, v142
	ds_read_b128 v[146:149], v76 offset:32
	v_fmac_f32_e32 v124, v118, v143
	v_fmac_f32_e32 v123, v118, v144
	v_fmac_f32_e32 v121, v118, v145
	ds_read_b128 v[142:145], v76 offset:48
	v_mul_f32_e32 v117, v117, v139
	s_waitcnt lgkmcnt(1)
	v_fmac_f32_e32 v140, v118, v146
	v_fmac_f32_e32 v138, v118, v147
	v_fmac_f32_e32 v137, v118, v148
	v_fmac_f32_e32 v133, v118, v149
	s_waitcnt lgkmcnt(0)
	v_fmac_f32_e32 v128, v118, v142
	global_store_short v[0:1], v120, off offset:1536
	v_mul_f32_e32 v120, v46, v117
	v_cvt_pk_bf16_f32 v117, v120, v5
	ds_read_b128 v[146:149], v77
	v_fmac_f32_e32 v136, v118, v143
	v_fmac_f32_e32 v131, v118, v144
	v_fmac_f32_e32 v126, v118, v145
	ds_read_b128 v[142:145], v77 offset:16
	s_waitcnt lgkmcnt(1)
	v_fmac_f32_e32 v135, v120, v146
	v_fmac_f32_e32 v130, v120, v147
	v_fmac_f32_e32 v129, v120, v148
	v_fmac_f32_e32 v125, v120, v149
	s_waitcnt lgkmcnt(0)
	v_fmac_f32_e32 v122, v120, v142
	ds_read_b128 v[146:149], v77 offset:32
	v_fmac_f32_e32 v124, v120, v143
	v_fmac_f32_e32 v123, v120, v144
	v_fmac_f32_e32 v121, v120, v145
	ds_read_b128 v[142:145], v77 offset:48
	v_mul_f32_e32 v116, v116, v139
	global_store_short v[0:1], v117, off offset:1664
	v_mul_f32_e32 v127, v47, v116
	v_cvt_pk_bf16_f32 v141, v127, v5
	ds_read_b128 v[116:119], v78
	s_waitcnt lgkmcnt(1)
	v_fmac_f32_e32 v128, v120, v142
	v_fmac_f32_e32 v136, v120, v143
	v_fmac_f32_e32 v131, v120, v144
	v_fmac_f32_e32 v126, v120, v145
	ds_read_b128 v[142:145], v78 offset:16
	s_waitcnt lgkmcnt(1)
	v_fmac_f32_e32 v135, v127, v116
	v_fmac_f32_e32 v130, v127, v117
	v_fmac_f32_e32 v129, v127, v118
	v_fmac_f32_e32 v125, v127, v119
	ds_read_b128 v[116:119], v78 offset:32
	s_waitcnt lgkmcnt(1)
	v_fmac_f32_e32 v122, v127, v142
	v_fmac_f32_e32 v124, v127, v143
	v_fmac_f32_e32 v123, v127, v144
	v_fmac_f32_e32 v121, v127, v145
	ds_read_b128 v[142:145], v78 offset:48
	v_fmac_f32_e32 v140, v120, v146
	v_fmac_f32_e32 v138, v120, v147
	v_fmac_f32_e32 v137, v120, v148
	v_fmac_f32_e32 v133, v120, v149
	v_mul_f32_e32 v33, v33, v139
	s_waitcnt lgkmcnt(1)
	v_fmac_f32_e32 v140, v127, v116
	v_fmac_f32_e32 v138, v127, v117
	v_fmac_f32_e32 v137, v127, v118
	v_fmac_f32_e32 v133, v127, v119
	global_store_short v[0:1], v141, off offset:1792
	v_mul_f32_e32 v33, v48, v33
	v_cvt_pk_bf16_f32 v120, v33, v5
	ds_read_b128 v[116:119], v79
	s_waitcnt lgkmcnt(1)
	v_fmac_f32_e32 v128, v127, v142
	v_fmac_f32_e32 v136, v127, v143
	v_fmac_f32_e32 v131, v127, v144
	v_fmac_f32_e32 v126, v127, v145
	ds_read_b128 v[142:145], v79 offset:16
	s_waitcnt lgkmcnt(1)
	v_fmac_f32_e32 v135, v33, v116
	v_fmac_f32_e32 v130, v33, v117
	v_fmac_f32_e32 v129, v33, v118
	v_fmac_f32_e32 v125, v33, v119
	ds_read_b128 v[116:119], v79 offset:32
	s_waitcnt lgkmcnt(1)
	v_fmac_f32_e32 v122, v33, v142
	v_fmac_f32_e32 v124, v33, v143
	v_fmac_f32_e32 v123, v33, v144
	v_fmac_f32_e32 v121, v33, v145
	ds_read_b128 v[142:145], v79 offset:48
	s_waitcnt lgkmcnt(1)
	v_fmac_f32_e32 v140, v33, v116
	v_fmac_f32_e32 v138, v33, v117
	v_fmac_f32_e32 v137, v33, v118
	v_fmac_f32_e32 v133, v33, v119
	s_waitcnt lgkmcnt(0)
	v_fmac_f32_e32 v128, v33, v142
	v_fmac_f32_e32 v136, v33, v143
	v_fmac_f32_e32 v131, v33, v144
	v_fmac_f32_e32 v126, v33, v145
	v_cndmask_b32_e64 v33, v135, v140, s[26:27]
	ds_bpermute_b32 v33, v19, v33
	v_cndmask_b32_e64 v117, v130, v138, s[26:27]
	ds_bpermute_b32 v117, v19, v117
	v_cndmask_b32_e64 v118, v129, v137, s[26:27]
	ds_bpermute_b32 v118, v19, v118
	v_cndmask_b32_e64 v116, v140, v135, s[26:27]
	s_waitcnt lgkmcnt(2)
	v_add_f32_e32 v33, v116, v33
	v_cndmask_b32_e64 v116, v138, v130, s[26:27]
	s_waitcnt lgkmcnt(1)
	v_add_f32_e32 v116, v116, v117
	v_cndmask_b32_e64 v117, v137, v129, s[26:27]
	s_waitcnt lgkmcnt(0)
	v_add_f32_e32 v117, v117, v118
	v_cndmask_b32_e64 v118, v125, v133, s[26:27]
	v_cndmask_b32_e64 v119, v133, v125, s[26:27]
	ds_bpermute_b32 v118, v19, v118
	v_cndmask_b32_e64 v125, v122, v128, s[26:27]
	ds_bpermute_b32 v125, v19, v125
	v_cndmask_b32_e64 v127, v124, v136, s[26:27]
	ds_bpermute_b32 v127, v19, v127
	s_waitcnt lgkmcnt(2)
	v_add_f32_e32 v118, v119, v118
	v_cndmask_b32_e64 v119, v128, v122, s[26:27]
	s_waitcnt lgkmcnt(1)
	v_add_f32_e32 v119, v119, v125
	v_cndmask_b32_e64 v122, v136, v124, s[26:27]
	v_cndmask_b32_e64 v124, v123, v131, s[26:27]
	v_cndmask_b32_e64 v125, v121, v126, s[26:27]
	ds_bpermute_b32 v124, v19, v124
	ds_bpermute_b32 v125, v19, v125
	v_cndmask_b32_e64 v123, v131, v123, s[26:27]
	v_cndmask_b32_e64 v121, v126, v121, s[26:27]
	s_waitcnt lgkmcnt(2)
	v_add_f32_e32 v122, v122, v127
	s_waitcnt lgkmcnt(1)
	v_add_f32_e32 v123, v123, v124
	s_waitcnt lgkmcnt(0)
; __device__ __forceinline__ void p0_phase(const Args& a, LAS unsigned char* lds, int tid, int lane, int wave) {
;     ...
;                   for (int k = 0; k < 2; ++k) { const float send = b3 ? f[k] : f[k + 2], keep = b3 ? f[k + 2] : f[k]; f[k] = keep + __shfl_xor(send, 8); }
;                   const bool b2 = lane & 4;
;                   { const float send = b2 ? f[0] : f[1], keep = b2 ? f[1] : f[0]; f[0] = keep + __shfl_xor(send, 4); }
;                   f[0] += __shfl_xor(f[0], 2); f[0] += __shfl_xor(f[0], 1); }
;                 if ((lane & 3) == 0) { const int hh = ((lane >> 5) & 1) * 8 + ((lane >> 4) & 1) * 4 + ((lane >> 3) & 1) * 2 + ((lane >> 2) & 1);
;                     const float z = f[0] + bfg[hh]; const float lg = fminf(z, 0.f) - log1pf(expf(-fabsf(z)));
;                     lf[rl * 16 + hh] = lg;
;                     if (row < MP) a.out[O_LFP + (size_t)row * NH + hh] = lg; else a.out[O_LFS + (size_t)(row - MP) * NH + hh] = lg; }
	v_add_f32_e32 v121, v121, v125
	v_cndmask_b32_e64 v127, v33, v119, s[28:29]
	v_cndmask_b32_e64 v33, v119, v33, s[28:29]
	v_cndmask_b32_e64 v119, v116, v122, s[28:29]
	v_cndmask_b32_e64 v116, v122, v116, s[28:29]
	v_cndmask_b32_e64 v122, v117, v123, s[28:29]
	v_cndmask_b32_e64 v124, v118, v121, s[28:29]
	ds_bpermute_b32 v127, v18, v127
	ds_bpermute_b32 v119, v18, v119
	ds_bpermute_b32 v122, v18, v122
	ds_bpermute_b32 v124, v18, v124
	v_cndmask_b32_e64 v117, v123, v117, s[28:29]
	v_cndmask_b32_e64 v118, v121, v118, s[28:29]
	s_waitcnt lgkmcnt(3)
	v_add_f32_e32 v33, v33, v127
	s_waitcnt lgkmcnt(2)
	v_add_f32_e32 v116, v116, v119
	s_waitcnt lgkmcnt(1)
	v_add_f32_e32 v117, v117, v122
	s_waitcnt lgkmcnt(0)
	v_add_f32_e32 v118, v118, v124
	v_cndmask_b32_e64 v119, v33, v117, s[30:31]
	v_cndmask_b32_e64 v121, v116, v118, s[30:31]
	ds_bpermute_b32 v119, v17, v119
	ds_bpermute_b32 v121, v17, v121
	v_cndmask_b32_e64 v33, v117, v33, s[30:31]
	v_cndmask_b32_e64 v116, v118, v116, s[30:31]
	global_store_short v[0:1], v120, off offset:1920
	s_waitcnt lgkmcnt(1)
	v_add_f32_e32 v33, v33, v119
	s_waitcnt lgkmcnt(0)
	v_add_f32_e32 v116, v116, v121
	v_cndmask_b32_e64 v117, v33, v116, s[34:35]
	ds_bpermute_b32 v117, v4, v117
	v_cndmask_b32_e64 v33, v116, v33, s[34:35]
	s_waitcnt lgkmcnt(0)
	v_add_f32_e32 v33, v33, v117
	ds_bpermute_b32 v116, v3, v33
	s_waitcnt lgkmcnt(0)
	v_add_f32_e32 v116, v33, v116
	ds_bpermute_b32 v117, v2, v116
	v_lshlrev_b32_e32 v33, 2, v8
	s_and_saveexec_b64 s[92:93], s[36:37]
	s_cbranch_execz .LBB0_35
	global_load_dword v0, v[10:11], off
	s_waitcnt lgkmcnt(0)
	v_add_f32_e32 v1, v116, v117
	s_add_i32 s11, s0, 0xffffc000
	s_cmpk_lt_i32 s0, 0x4000
	s_cselect_b32 s1, s1, 0
	s_cselect_b32 s0, s0, s11
	s_cselect_b32 s11, s7, 0xcd04000
	s_lshl_b64 s[0:1], s[0:1], 6
	s_add_u32 s0, s86, s0
	s_addc_u32 s1, s87, s1
	s_add_u32 s0, s0, s11
	v_lshl_add_u32 v116, s10, 6, v51
	s_addc_u32 s1, s1, 0
	s_waitcnt vmcnt(0)
	v_add_f32_e32 v0, v1, v0
	v_mul_f32_e64 v1, |v0|, s70
	v_fma_f32 v117, |v0|, s70, -v1
	v_rndne_f32_e32 v118, v1
	v_fma_f32 v117, |v0|, s71, v117
	v_sub_f32_e32 v1, v1, v118
	v_add_f32_e32 v1, v1, v117
	v_cvt_i32_f32_e32 v118, v118
	v_exp_f32_e32 v1, v1
	v_cmp_ngt_f32_e64 vcc, |v0|, s50
	v_min_f32_e32 v117, 0, v0
	v_ldexp_f32 v1, v1, v118
	v_cndmask_b32_e32 v1, 0, v1, vcc
	v_cmp_nlt_f32_e64 vcc, |v0|, s94
	s_nop 1
	v_cndmask_b32_e32 v118, v63, v1, vcc
	v_add_f32_e32 v119, 1.0, v118
	v_add_f32_e32 v120, -1.0, v119
	v_frexp_mant_f32_e32 v121, v119
	v_cvt_f64_f32_e32 v[0:1], v119
	v_sub_f32_e32 v122, v120, v119
	v_frexp_exp_i32_f64_e32 v0, v[0:1]
	v_cmp_gt_f32_e32 vcc, s4, v121
	v_sub_f32_e32 v120, v118, v120
	v_add_f32_e32 v1, 1.0, v122
	v_subbrev_co_u32_e32 v0, vcc, 0, v0, vcc
	v_add_f32_e32 v1, v120, v1
	v_sub_u32_e32 v120, 0, v0
	v_cvt_f32_i32_e32 v0, v0
	v_ldexp_f32 v119, v119, v120
	v_ldexp_f32 v1, v1, v120
	v_add_f32_e32 v120, -1.0, v119
	v_add_f32_e32 v121, 1.0, v119
	v_add_f32_e32 v122, 1.0, v120
	v_add_f32_e32 v123, -1.0, v121
	v_sub_f32_e32 v122, v119, v122
	v_sub_f32_e32 v119, v119, v123
	v_mul_f32_e32 v123, 0x3f317218, v0
	v_add_f32_e32 v122, v1, v122
	v_add_f32_e32 v1, v1, v119
	v_fma_f32 v119, v0, s5, -v123
	v_add_f32_e32 v124, v120, v122
	v_add_f32_e32 v125, v121, v1
	v_fmac_f32_e32 v119, 0xb102e308, v0
	v_sub_f32_e32 v0, v120, v124
	v_sub_f32_e32 v120, v121, v125
	v_rcp_f32_e32 v121, v125
	v_add_f32_e32 v126, v123, v119
	v_add_f32_e32 v1, v1, v120
	v_sub_f32_e32 v120, v126, v123
	v_sub_f32_e32 v119, v119, v120
	v_mul_f32_e32 v120, v124, v121
	v_add_f32_e32 v0, v122, v0
	v_mul_f32_e32 v122, v125, v120
	v_fma_f32 v123, v120, v125, -v122
	v_fmac_f32_e32 v123, v120, v1
	v_add_f32_e32 v127, v122, v123
	v_sub_f32_e32 v128, v124, v127
	v_sub_f32_e32 v122, v127, v122
	v_sub_f32_e32 v124, v124, v128
	v_sub_f32_e32 v122, v122, v123
	v_sub_f32_e32 v123, v124, v127
	v_add_f32_e32 v0, v0, v123
	v_add_f32_e32 v0, v122, v0
	v_add_f32_e32 v122, v128, v0
	v_mul_f32_e32 v123, v121, v122
	v_sub_f32_e32 v124, v128, v122
	v_mul_f32_e32 v127, v125, v123
	v_add_f32_e32 v0, v0, v124
	v_add_f32_e32 v124, v120, v123
	v_fma_f32 v125, v123, v125, -v127
	v_sub_f32_e32 v120, v124, v120
	v_fmac_f32_e32 v125, v123, v1
	v_sub_f32_e32 v1, v123, v120
	v_add_f32_e32 v120, v127, v125
	v_sub_f32_e32 v123, v120, v127
	v_sub_f32_e32 v127, v122, v120
	v_sub_f32_e32 v122, v122, v127
	v_sub_f32_e32 v120, v122, v120
	v_sub_f32_e32 v123, v123, v125
	v_add_f32_e32 v0, v0, v120
	v_add_f32_e32 v0, v123, v0
	v_add_f32_e32 v0, v127, v0
	v_mul_f32_e32 v0, v121, v0
	v_add_f32_e32 v0, v1, v0
	v_add_f32_e32 v1, v124, v0
	v_mul_f32_e32 v120, v1, v1
	v_fmamk_f32 v123, v120, 0x3e9b6dac, v62
	v_sub_f32_e32 v121, v1, v124
	v_ldexp_f32 v122, v1, 1
	v_mul_f32_e32 v1, v1, v120
	v_fmaak_f32 v120, v120, v123, 0x3f2aaada
	v_mul_f32_e32 v1, v1, v120
	v_add_f32_e32 v120, v122, v1
	v_sub_f32_e32 v0, v0, v121
	v_sub_f32_e32 v121, v120, v122
	v_ldexp_f32 v0, v0, 1
	v_sub_f32_e32 v1, v1, v121
	v_add_f32_e32 v0, v0, v1
	v_add_f32_e32 v1, v120, v0
	v_sub_f32_e32 v120, v1, v120
	v_add_f32_e32 v121, v126, v1
	v_sub_f32_e32 v0, v0, v120
	v_sub_f32_e32 v120, v121, v126
	v_sub_f32_e32 v122, v121, v120
	v_sub_f32_e32 v1, v1, v120
	v_add_f32_e32 v120, v119, v0
	v_sub_f32_e32 v122, v126, v122
	v_sub_f32_e32 v123, v120, v119
	v_add_f32_e32 v1, v1, v122
	v_sub_f32_e32 v122, v120, v123
	v_sub_f32_e32 v0, v0, v123
	v_sub_f32_e32 v119, v119, v122
	v_add_f32_e32 v1, v120, v1
	v_add_f32_e32 v0, v0, v119
	v_add_f32_e32 v119, v121, v1
	v_sub_f32_e32 v120, v119, v121
	v_sub_f32_e32 v1, v1, v120
	v_add_f32_e32 v0, v0, v1
	v_add_f32_e32 v0, v119, v0
	v_cmp_neq_f32_e32 vcc, s95, v118
	s_nop 1
	v_cndmask_b32_e32 v0, v63, v0, vcc
	v_cmp_lt_f32_e64 vcc, |v118|, s6
	s_nop 1
	v_cndmask_b32_e32 v0, v0, v118, vcc
	v_sub_f32_e32 v0, v117, v0
	ds_write_b32 v116, v0
	global_store_dword v33, v0, s[0:1]
; #define LAS __attribute__((address_space(3)))
; __device__ __forceinline__ unsigned cvt_pk_bf16(float lo, float hi) { unsigned r; asm volatile("v_cvt_pk_bf16_f32 %0, %1, %2" : "=v"(r) : "v"(lo), "v"(hi)); return r; }
; __device__ __forceinline__ void p0_phase(const Args& a, LAS unsigned char* lds, int tid, int lane, int wave) {
;     ...
;                 for (int u = 0; u < 4; ++u) {
;                 const int rl = wave * 8 + i4 * 4 + u, row = c * 64 + rl;
;                 float ss = 0.f;
; #pragma unroll
;                 for (int j = 0; j < 16; ++j) ss += xa[u][j] * xa[u][j];
;                 const float rstd = 1.0f / sqrtf(wave_sum(ss) * (1.f / D) + EPS);
;                 float f[16];
; #pragma unroll
;                 for (int h = 0; h < 16; ++h) f[h] = 0.f;
; #pragma unroll
;                 for (int j = 0; j < 16; ++j) { const float xn = xa[u][j] * rstd * gm[j];
;                     XN[(size_t)row * D + lane + 64 * j] = (bf16_t)(cvt_pk_bf16(xn, 0.f) & 0xffffu);
;                     const LAS f32x4* wp = (const LAS f32x4*)(wfl + (lane + 64 * j) * 16);
; #pragma unroll
;                     for (int q = 0; q < 4; ++q) { const f32x4 w = wp[q]; f[4 * q + 0] += xn * w[0]; f[4 * q + 1] += xn * w[1]; f[4 * q + 2] += xn * w[2]; f[4 * q + 3] += xn * w[3]; } }
.LBB0_35:
	s_or_b64 exec, exec, s[92:93]
	s_waitcnt vmcnt(59)
	v_mul_f32_e32 v0, v115, v115
	v_fmac_f32_e32 v0, v111, v111
	s_waitcnt vmcnt(58)
	v_fmac_f32_e32 v0, v114, v114
	s_waitcnt vmcnt(57)
	v_fmac_f32_e32 v0, v113, v113
	s_waitcnt vmcnt(56)
	v_fmac_f32_e32 v0, v112, v112
	s_waitcnt vmcnt(55)
	v_fmac_f32_e32 v0, v110, v110
	s_waitcnt vmcnt(54)
	v_fmac_f32_e32 v0, v109, v109
	s_waitcnt vmcnt(53)
	v_fmac_f32_e32 v0, v108, v108
	s_waitcnt vmcnt(52)
	v_fmac_f32_e32 v0, v107, v107
	s_waitcnt vmcnt(51)
	v_fmac_f32_e32 v0, v106, v106
	s_waitcnt vmcnt(50)
	v_fmac_f32_e32 v0, v105, v105
	s_waitcnt vmcnt(49)
	v_fmac_f32_e32 v0, v104, v104
	s_waitcnt vmcnt(48)
	v_fmac_f32_e32 v0, v103, v103
	s_waitcnt vmcnt(47)
	v_fmac_f32_e32 v0, v102, v102
	s_waitcnt vmcnt(46)
	v_fmac_f32_e32 v0, v101, v101
	v_fmac_f32_e32 v0, v100, v100
	ds_bpermute_b32 v1, v2, v0
	s_or_b32 s11, s10, 1
	s_add_i32 s92, s11, s45
	s_ashr_i32 s93, s92, 31
	s_lshl_b64 s[12:13], s[92:93], 11
	s_waitcnt lgkmcnt(0)
	v_add_f32_e32 v0, v0, v1
	ds_bpermute_b32 v1, v3, v0
	s_waitcnt lgkmcnt(0)
	v_add_f32_e32 v0, v0, v1
	ds_bpermute_b32 v1, v4, v0
	s_waitcnt lgkmcnt(0)
	v_add_f32_e32 v0, v0, v1
	ds_bpermute_b32 v1, v17, v0
	s_waitcnt lgkmcnt(0)
	v_add_f32_e32 v0, v0, v1
	ds_bpermute_b32 v1, v18, v0
	s_waitcnt lgkmcnt(0)
	v_add_f32_e32 v0, v0, v1
	ds_bpermute_b32 v1, v19, v0
	s_waitcnt lgkmcnt(0)
	v_add_f32_e32 v0, v0, v1
	v_fmamk_f32 v0, v0, 0x3a800000, v60
	v_mul_f32_e32 v1, 0x4f800000, v0
	v_cmp_gt_f32_e32 vcc, s49, v0
	s_nop 1
	v_cndmask_b32_e32 v0, v0, v1, vcc
	v_sqrt_f32_e32 v1, v0
	s_nop 0
	v_add_u32_e32 v116, -1, v1
	v_add_u32_e32 v117, 1, v1
	v_fma_f32 v118, -v116, v1, v0
	v_fma_f32 v119, -v117, v1, v0
	v_cmp_ge_f32_e64 s[0:1], 0, v118
	s_nop 1
	v_cndmask_b32_e64 v1, v1, v116, s[0:1]
	v_cmp_lt_f32_e64 s[0:1], 0, v119
	s_nop 1
	v_cndmask_b32_e64 v1, v1, v117, s[0:1]
	v_mul_f32_e32 v116, 0x37800000, v1
	v_cndmask_b32_e32 v1, v1, v116, vcc
	v_cmp_class_f32_e32 vcc, v0, v61
	s_nop 1
	v_cndmask_b32_e32 v116, v1, v0, vcc
	v_div_scale_f32 v117, s[0:1], v116, v116, 1.0
	v_rcp_f32_e32 v118, v117
	v_div_scale_f32 v119, vcc, 1.0, v116, 1.0
	v_lshl_add_u64 v[0:1], v[6:7], 0, s[12:13]
	v_fma_f32 v120, -v117, v118, 1.0
	v_fmac_f32_e32 v118, v120, v118
	v_mul_f32_e32 v120, v119, v118
	v_fma_f32 v121, -v117, v120, v119
	v_fmac_f32_e32 v120, v121, v118
	v_fma_f32 v117, -v117, v120, v119
	v_div_fmas_f32 v117, v117, v118, v120
	v_div_fixup_f32 v131, v117, v116, 1.0
	v_mul_f32_e32 v111, v111, v131
	v_mul_f32_e32 v133, v9, v111
	v_cvt_pk_bf16_f32 v111, v133, v5
	v_mul_f32_e32 v115, v115, v131
	global_store_short v[0:1], v111, off
	s_waitcnt lgkmcnt(0)
	v_fma_f32 v129, v160, v133, 0
	v_fma_f32 v125, v161, v133, 0
	v_fma_f32 v124, v162, v133, 0
	v_fma_f32 v123, v163, v133, 0
	s_waitcnt lgkmcnt(0)
	v_fma_f32 v119, v164, v133, 0
	v_fma_f32 v118, v165, v133, 0
	v_fma_f32 v117, v166, v133, 0
	v_fma_f32 v111, v167, v133, 0
	s_waitcnt lgkmcnt(0)
	v_fma_f32 v130, v168, v133, 0
	v_fma_f32 v128, v169, v133, 0
	v_fma_f32 v127, v170, v133, 0
	v_fma_f32 v126, v171, v133, 0
	s_waitcnt lgkmcnt(0)
	v_fma_f32 v122, v133, v172, 0
	v_fma_f32 v121, v133, v173, 0
	v_fma_f32 v120, v133, v174, 0
	v_fma_f32 v116, v133, v175, 0
	v_mul_f32_e32 v115, v34, v115
	v_cvt_pk_bf16_f32 v133, v115, v5
	global_store_short v[0:1], v133, off offset:128
	v_mul_f32_e32 v114, v114, v131
	v_mul_f32_e32 v114, v35, v114
	s_waitcnt lgkmcnt(0)
	v_fmac_f32_e32 v119, v115, v180
	v_fmac_f32_e32 v129, v115, v176
	v_fmac_f32_e32 v125, v115, v177
	v_fmac_f32_e32 v124, v115, v178
	v_fmac_f32_e32 v123, v115, v179
	v_fmac_f32_e32 v118, v115, v181
	v_fmac_f32_e32 v117, v115, v182
	v_fmac_f32_e32 v111, v115, v183
	s_waitcnt lgkmcnt(0)
	v_fmac_f32_e32 v130, v115, v184
	v_fmac_f32_e32 v128, v115, v185
	v_fmac_f32_e32 v127, v115, v186
	v_fmac_f32_e32 v126, v115, v187
	s_waitcnt lgkmcnt(0)
	v_fmac_f32_e32 v122, v115, v188
	v_fmac_f32_e32 v121, v115, v189
	v_fmac_f32_e32 v120, v115, v190
	v_fmac_f32_e32 v116, v115, v191
	v_cvt_pk_bf16_f32 v115, v114, v5
	global_store_short v[0:1], v115, off offset:256
	v_mul_f32_e32 v113, v113, v131
	v_mul_f32_e32 v113, v36, v113
	s_waitcnt lgkmcnt(0)
	v_fmac_f32_e32 v119, v114, v196
	v_fmac_f32_e32 v129, v114, v192
	v_fmac_f32_e32 v125, v114, v193
	v_fmac_f32_e32 v124, v114, v194
	v_fmac_f32_e32 v123, v114, v195
	v_fmac_f32_e32 v118, v114, v197
	v_fmac_f32_e32 v117, v114, v198
	v_fmac_f32_e32 v111, v114, v199
	s_waitcnt lgkmcnt(0)
	v_fmac_f32_e32 v130, v114, v200
	v_fmac_f32_e32 v128, v114, v201
	v_fmac_f32_e32 v127, v114, v202
	v_fmac_f32_e32 v126, v114, v203
	s_waitcnt lgkmcnt(0)
	v_fmac_f32_e32 v122, v114, v204
	v_fmac_f32_e32 v121, v114, v205
	v_fmac_f32_e32 v120, v114, v206
	v_fmac_f32_e32 v116, v114, v207
	v_cvt_pk_bf16_f32 v114, v113, v5
	global_store_short v[0:1], v114, off offset:384
	v_mul_f32_e32 v112, v112, v131
	v_mul_f32_e32 v133, v37, v112
	v_cvt_pk_bf16_f32 v135, v133, v5
	global_store_short v[0:1], v135, off offset:512
	s_waitcnt lgkmcnt(0)
	v_fmac_f32_e32 v129, v113, v208
	v_fmac_f32_e32 v125, v113, v209
	v_fmac_f32_e32 v124, v113, v210
	v_fmac_f32_e32 v123, v113, v211
	s_waitcnt lgkmcnt(0)
	v_fmac_f32_e32 v119, v113, v212
	v_fmac_f32_e32 v118, v113, v213
	v_fmac_f32_e32 v117, v113, v214
	v_fmac_f32_e32 v111, v113, v215
	s_waitcnt lgkmcnt(0)
	v_fmac_f32_e32 v130, v113, v216
	v_fmac_f32_e32 v128, v113, v217
	v_fmac_f32_e32 v127, v113, v218
	v_fmac_f32_e32 v126, v113, v219
	s_waitcnt lgkmcnt(0)
	v_fmac_f32_e32 v122, v113, v220
	v_fmac_f32_e32 v121, v113, v221
	v_fmac_f32_e32 v120, v113, v222
	v_fmac_f32_e32 v116, v113, v223
	v_mul_f32_e32 v110, v110, v131
	v_mul_f32_e32 v110, v38, v110
	s_waitcnt lgkmcnt(0)
; #define LAS __attribute__((address_space(3)))
; __device__ __forceinline__ unsigned cvt_pk_bf16(float lo, float hi) { unsigned r; asm volatile("v_cvt_pk_bf16_f32 %0, %1, %2" : "=v"(r) : "v"(lo), "v"(hi)); return r; }
; __device__ __forceinline__ void p0_phase(const Args& a, LAS unsigned char* lds, int tid, int lane, int wave) {
;     ...
;                 for (int j = 0; j < 16; ++j) { const float xn = xa[u][j] * rstd * gm[j];
;                     XN[(size_t)row * D + lane + 64 * j] = (bf16_t)(cvt_pk_bf16(xn, 0.f) & 0xffffu);
;                     const LAS f32x4* wp = (const LAS f32x4*)(wfl + (lane + 64 * j) * 16);
; #pragma unroll
;                     for (int q = 0; q < 4; ++q) { const f32x4 w = wp[q]; f[4 * q + 0] += xn * w[0]; f[4 * q + 1] += xn * w[1]; f[4 * q + 2] += xn * w[2]; f[4 * q + 3] += xn * w[3]; } }
	v_fmac_f32_e32 v119, v133, v228
	v_fmac_f32_e32 v129, v133, v224
	v_fmac_f32_e32 v125, v133, v225
	v_fmac_f32_e32 v124, v133, v226
	v_fmac_f32_e32 v123, v133, v227
	v_fmac_f32_e32 v118, v133, v229
	v_fmac_f32_e32 v117, v133, v230
	v_fmac_f32_e32 v111, v133, v231
	s_waitcnt lgkmcnt(0)
	v_fmac_f32_e32 v130, v133, v232
	v_fmac_f32_e32 v128, v133, v233
	v_fmac_f32_e32 v127, v133, v234
	v_fmac_f32_e32 v126, v133, v235
	s_waitcnt lgkmcnt(0)
	v_fmac_f32_e32 v122, v133, v236
	v_fmac_f32_e32 v121, v133, v237
	v_fmac_f32_e32 v120, v133, v238
	v_fmac_f32_e32 v116, v133, v239
	v_cvt_pk_bf16_f32 v133, v110, v5
	global_store_short v[0:1], v133, off offset:640
	ds_read_b128 v[144:147], v69 offset:48
	v_mul_f32_e32 v109, v109, v131
	v_mul_f32_e32 v109, v39, v109
	s_waitcnt lgkmcnt(1)
	v_fmac_f32_e32 v119, v110, v244
	v_fmac_f32_e32 v129, v110, v240
	v_fmac_f32_e32 v125, v110, v241
	v_fmac_f32_e32 v124, v110, v242
	v_fmac_f32_e32 v123, v110, v243
	v_fmac_f32_e32 v118, v110, v245
	v_fmac_f32_e32 v117, v110, v246
	v_fmac_f32_e32 v111, v110, v247
	s_waitcnt lgkmcnt(1)
	v_fmac_f32_e32 v130, v110, v248
	v_fmac_f32_e32 v128, v110, v249
	v_fmac_f32_e32 v127, v110, v250
	v_fmac_f32_e32 v126, v110, v251
	s_waitcnt lgkmcnt(0)
	v_fmac_f32_e32 v122, v110, v144
	v_fmac_f32_e32 v121, v110, v145
	v_fmac_f32_e32 v120, v110, v146
	v_fmac_f32_e32 v116, v110, v147
	v_cvt_pk_bf16_f32 v110, v109, v5
	global_store_short v[0:1], v110, off offset:768
	ds_read_b128 v[112:115], v70
	ds_read_b128 v[136:139], v70 offset:16
	ds_read_b128 v[140:143], v70 offset:32
	ds_read_b128 v[144:147], v70 offset:48
	v_mul_f32_e32 v108, v108, v131
	v_mul_f32_e32 v108, v40, v108
	s_waitcnt lgkmcnt(2)
	v_fmac_f32_e32 v119, v109, v136
	v_fmac_f32_e32 v129, v109, v112
	v_fmac_f32_e32 v125, v109, v113
	v_fmac_f32_e32 v124, v109, v114
	v_fmac_f32_e32 v123, v109, v115
	v_fmac_f32_e32 v118, v109, v137
	v_fmac_f32_e32 v117, v109, v138
	v_fmac_f32_e32 v111, v109, v139
	s_waitcnt lgkmcnt(1)
	v_fmac_f32_e32 v130, v109, v140
	v_fmac_f32_e32 v128, v109, v141
	v_fmac_f32_e32 v127, v109, v142
	v_fmac_f32_e32 v126, v109, v143
	s_waitcnt lgkmcnt(0)
	v_fmac_f32_e32 v122, v109, v144
	v_fmac_f32_e32 v121, v109, v145
	v_fmac_f32_e32 v120, v109, v146
	v_fmac_f32_e32 v116, v109, v147
	v_cvt_pk_bf16_f32 v109, v108, v5
	global_store_short v[0:1], v109, off offset:896
	ds_read_b128 v[112:115], v71
	ds_read_b128 v[136:139], v71 offset:16
	ds_read_b128 v[140:143], v71 offset:32
	ds_read_b128 v[144:147], v71 offset:48
	v_mul_f32_e32 v107, v107, v131
	v_mul_f32_e32 v107, v41, v107
	s_waitcnt lgkmcnt(2)
	v_fmac_f32_e32 v119, v108, v136
	v_fmac_f32_e32 v129, v108, v112
	v_fmac_f32_e32 v125, v108, v113
	v_fmac_f32_e32 v124, v108, v114
	v_fmac_f32_e32 v123, v108, v115
	v_fmac_f32_e32 v118, v108, v137
	v_fmac_f32_e32 v117, v108, v138
	v_fmac_f32_e32 v111, v108, v139
	s_waitcnt lgkmcnt(1)
	v_fmac_f32_e32 v130, v108, v140
	v_fmac_f32_e32 v128, v108, v141
	v_fmac_f32_e32 v127, v108, v142
	v_fmac_f32_e32 v126, v108, v143
	s_waitcnt lgkmcnt(0)
	v_fmac_f32_e32 v122, v108, v144
	v_fmac_f32_e32 v121, v108, v145
	v_fmac_f32_e32 v120, v108, v146
	v_fmac_f32_e32 v116, v108, v147
	v_cvt_pk_bf16_f32 v108, v107, v5
	ds_read_b128 v[112:115], v72
	global_store_short v[0:1], v108, off offset:1024
	ds_read_b128 v[136:139], v72 offset:16
	ds_read_b128 v[140:143], v72 offset:32
	ds_read_b128 v[144:147], v72 offset:48
	v_mul_f32_e32 v106, v106, v131
	v_mul_f32_e32 v110, v42, v106
	s_waitcnt lgkmcnt(3)
	v_fmac_f32_e32 v129, v107, v112
	v_cvt_pk_bf16_f32 v112, v110, v5
	global_store_short v[0:1], v112, off offset:1152
	v_fmac_f32_e32 v125, v107, v113
	v_fmac_f32_e32 v124, v107, v114
	v_fmac_f32_e32 v123, v107, v115
	s_waitcnt lgkmcnt(2)
	v_fmac_f32_e32 v119, v107, v136
	v_fmac_f32_e32 v118, v107, v137
	v_fmac_f32_e32 v117, v107, v138
	v_fmac_f32_e32 v111, v107, v139
	s_waitcnt lgkmcnt(1)
	v_fmac_f32_e32 v130, v107, v140
	v_fmac_f32_e32 v128, v107, v141
	v_fmac_f32_e32 v127, v107, v142
	v_fmac_f32_e32 v126, v107, v143
	s_waitcnt lgkmcnt(0)
	v_fmac_f32_e32 v122, v107, v144
	v_fmac_f32_e32 v121, v107, v145
	v_fmac_f32_e32 v120, v107, v146
	v_fmac_f32_e32 v116, v107, v147
	ds_read_b128 v[106:109], v73
	ds_read_b128 v[112:115], v73 offset:16
	ds_read_b128 v[136:139], v73 offset:32
	ds_read_b128 v[140:143], v73 offset:48
	v_mul_f32_e32 v105, v105, v131
	v_mul_f32_e32 v105, v43, v105
	s_waitcnt lgkmcnt(2)
	v_fmac_f32_e32 v119, v110, v112
	v_fmac_f32_e32 v129, v110, v106
	v_fmac_f32_e32 v125, v110, v107
	v_fmac_f32_e32 v124, v110, v108
	v_fmac_f32_e32 v123, v110, v109
	v_fmac_f32_e32 v118, v110, v113
	v_fmac_f32_e32 v117, v110, v114
	v_fmac_f32_e32 v111, v110, v115
	s_waitcnt lgkmcnt(1)
	v_fmac_f32_e32 v130, v110, v136
	v_fmac_f32_e32 v128, v110, v137
	v_fmac_f32_e32 v127, v110, v138
	v_fmac_f32_e32 v126, v110, v139
	s_waitcnt lgkmcnt(0)
	v_fmac_f32_e32 v122, v110, v140
	v_fmac_f32_e32 v121, v110, v141
	v_fmac_f32_e32 v120, v110, v142
	v_fmac_f32_e32 v116, v110, v143
	v_cvt_pk_bf16_f32 v110, v105, v5
	ds_read_b128 v[106:109], v74
	global_store_short v[0:1], v110, off offset:1280
	ds_read_b128 v[112:115], v74 offset:16
	ds_read_b128 v[136:139], v74 offset:32
	ds_read_b128 v[140:143], v74 offset:48
	v_mul_f32_e32 v104, v104, v131
	v_mul_f32_e32 v103, v103, v131
	s_waitcnt lgkmcnt(3)
	v_fmac_f32_e32 v124, v105, v108
	v_fmac_f32_e32 v123, v105, v109
	v_mul_f32_e32 v108, v44, v104
	v_cvt_pk_bf16_f32 v109, v108, v5
	global_store_short v[0:1], v109, off offset:1408
	v_fmac_f32_e32 v129, v105, v106
	v_fmac_f32_e32 v125, v105, v107
	s_waitcnt lgkmcnt(2)
	v_fmac_f32_e32 v119, v105, v112
	v_fmac_f32_e32 v118, v105, v113
	v_fmac_f32_e32 v117, v105, v114
	v_fmac_f32_e32 v111, v105, v115
	s_waitcnt lgkmcnt(1)
; #define LAS __attribute__((address_space(3)))
; __device__ __forceinline__ unsigned cvt_pk_bf16(float lo, float hi) { unsigned r; asm volatile("v_cvt_pk_bf16_f32 %0, %1, %2" : "=v"(r) : "v"(lo), "v"(hi)); return r; }
; __device__ __forceinline__ void p0_phase(const Args& a, LAS unsigned char* lds, int tid, int lane, int wave) {
;     ...
;                 for (int j = 0; j < 16; ++j) { const float xn = xa[u][j] * rstd * gm[j];
;                     XN[(size_t)row * D + lane + 64 * j] = (bf16_t)(cvt_pk_bf16(xn, 0.f) & 0xffffu);
;                     const LAS f32x4* wp = (const LAS f32x4*)(wfl + (lane + 64 * j) * 16);
; #pragma unroll
;                     for (int q = 0; q < 4; ++q) { const f32x4 w = wp[q]; f[4 * q + 0] += xn * w[0]; f[4 * q + 1] += xn * w[1]; f[4 * q + 2] += xn * w[2]; f[4 * q + 3] += xn * w[3]; } }
;                 { const bool b5 = lane & 32;
; #pragma unroll
;                   for (int k = 0; k < 8; ++k) { const float send = b5 ? f[k] : f[k + 8], keep = b5 ? f[k + 8] : f[k]; f[k] = keep + __shfl_xor(send, 32); }
;                   const bool b4 = lane & 16;
; #pragma unroll
;                   for (int k = 0; k < 4; ++k) { const float send = b4 ? f[k] : f[k + 4], keep = b4 ? f[k + 4] : f[k]; f[k] = keep + __shfl_xor(send, 16); }
;                   const bool b3 = lane & 8;
; #pragma unroll
;                   for (int k = 0; k < 2; ++k) { const float send = b3 ? f[k] : f[k + 2], keep = b3 ? f[k + 2] : f[k]; f[k] = keep + __shfl_xor(send, 8); }
	v_fmac_f32_e32 v130, v105, v136
	v_fmac_f32_e32 v128, v105, v137
	v_fmac_f32_e32 v127, v105, v138
	v_fmac_f32_e32 v126, v105, v139
	s_waitcnt lgkmcnt(0)
	v_fmac_f32_e32 v122, v105, v140
	v_fmac_f32_e32 v121, v105, v141
	v_fmac_f32_e32 v120, v105, v142
	v_fmac_f32_e32 v116, v105, v143
	ds_read_b128 v[104:107], v75
	ds_read_b128 v[112:115], v75 offset:16
	ds_read_b128 v[136:139], v75 offset:32
	ds_read_b128 v[140:143], v75 offset:48
	v_mul_f32_e32 v103, v45, v103
	v_mul_f32_e32 v102, v102, v131
	s_waitcnt lgkmcnt(2)
	v_fmac_f32_e32 v119, v108, v112
	v_fmac_f32_e32 v129, v108, v104
	v_fmac_f32_e32 v125, v108, v105
	v_fmac_f32_e32 v124, v108, v106
	v_fmac_f32_e32 v123, v108, v107
	v_fmac_f32_e32 v118, v108, v113
	v_fmac_f32_e32 v117, v108, v114
	v_fmac_f32_e32 v111, v108, v115
	s_waitcnt lgkmcnt(1)
	v_fmac_f32_e32 v130, v108, v136
	v_fmac_f32_e32 v128, v108, v137
	v_fmac_f32_e32 v127, v108, v138
	v_fmac_f32_e32 v126, v108, v139
	s_waitcnt lgkmcnt(0)
	v_fmac_f32_e32 v122, v108, v140
	v_fmac_f32_e32 v121, v108, v141
	v_fmac_f32_e32 v120, v108, v142
	v_fmac_f32_e32 v116, v108, v143
	v_cvt_pk_bf16_f32 v108, v103, v5
	ds_read_b128 v[104:107], v76
	global_store_short v[0:1], v108, off offset:1536
	ds_read_b128 v[112:115], v76 offset:16
	ds_read_b128 v[136:139], v76 offset:32
	ds_read_b128 v[140:143], v76 offset:48
	v_mul_f32_e32 v110, v46, v102
	v_mul_f32_e32 v101, v101, v131
	s_waitcnt lgkmcnt(3)
	v_fmac_f32_e32 v124, v103, v106
	v_cvt_pk_bf16_f32 v106, v110, v5
	global_store_short v[0:1], v106, off offset:1664
	v_fmac_f32_e32 v129, v103, v104
	v_fmac_f32_e32 v125, v103, v105
	v_fmac_f32_e32 v123, v103, v107
	s_waitcnt lgkmcnt(2)
	v_fmac_f32_e32 v119, v103, v112
	v_fmac_f32_e32 v118, v103, v113
	v_fmac_f32_e32 v117, v103, v114
	v_fmac_f32_e32 v111, v103, v115
	s_waitcnt lgkmcnt(1)
	v_fmac_f32_e32 v130, v103, v136
	v_fmac_f32_e32 v128, v103, v137
	v_fmac_f32_e32 v127, v103, v138
	v_fmac_f32_e32 v126, v103, v139
	s_waitcnt lgkmcnt(0)
	v_fmac_f32_e32 v122, v103, v140
	v_fmac_f32_e32 v121, v103, v141
	v_fmac_f32_e32 v120, v103, v142
	v_fmac_f32_e32 v116, v103, v143
	ds_read_b128 v[102:105], v77
	ds_read_b128 v[106:109], v77 offset:16
	ds_read_b128 v[112:115], v77 offset:32
	ds_read_b128 v[136:139], v77 offset:48
	v_mul_f32_e32 v100, v100, v131
	s_waitcnt lgkmcnt(2)
	v_fmac_f32_e32 v119, v110, v106
	v_fmac_f32_e32 v129, v110, v102
	v_fmac_f32_e32 v125, v110, v103
	v_fmac_f32_e32 v124, v110, v104
	v_fmac_f32_e32 v123, v110, v105
	v_fmac_f32_e32 v118, v110, v107
	v_fmac_f32_e32 v117, v110, v108
	v_fmac_f32_e32 v111, v110, v109
	s_waitcnt lgkmcnt(1)
	v_fmac_f32_e32 v130, v110, v112
	v_fmac_f32_e32 v128, v110, v113
	v_fmac_f32_e32 v127, v110, v114
	v_fmac_f32_e32 v126, v110, v115
	s_waitcnt lgkmcnt(0)
	v_fmac_f32_e32 v122, v110, v136
	v_fmac_f32_e32 v121, v110, v137
	v_fmac_f32_e32 v120, v110, v138
	v_fmac_f32_e32 v116, v110, v139
	v_mul_f32_e32 v110, v47, v101
	v_cvt_pk_bf16_f32 v101, v110, v5
	ds_read_b128 v[102:105], v78
	global_store_short v[0:1], v101, off offset:1792
	ds_read_b128 v[106:109], v78 offset:16
	ds_read_b128 v[112:115], v78 offset:32
	ds_read_b128 v[136:139], v78 offset:48
	s_waitcnt lgkmcnt(3)
	v_fmac_f32_e32 v129, v110, v102
	v_fmac_f32_e32 v125, v110, v103
	s_waitcnt lgkmcnt(2)
	v_fmac_f32_e32 v117, v110, v108
	v_fmac_f32_e32 v111, v110, v109
	v_mul_f32_e32 v108, v48, v100
	v_cvt_pk_bf16_f32 v109, v108, v5
	ds_read_b128 v[100:103], v79
	v_fmac_f32_e32 v124, v110, v104
	v_fmac_f32_e32 v123, v110, v105
	v_fmac_f32_e32 v119, v110, v106
	v_fmac_f32_e32 v118, v110, v107
	s_waitcnt lgkmcnt(2)
	v_fmac_f32_e32 v130, v110, v112
	v_fmac_f32_e32 v128, v110, v113
	v_fmac_f32_e32 v127, v110, v114
	v_fmac_f32_e32 v126, v110, v115
	s_waitcnt lgkmcnt(1)
	v_fmac_f32_e32 v122, v110, v136
	v_fmac_f32_e32 v121, v110, v137
	v_fmac_f32_e32 v120, v110, v138
	v_fmac_f32_e32 v116, v110, v139
	ds_read_b128 v[104:107], v79 offset:16
	ds_read_b128 v[112:115], v79 offset:32
	ds_read_b128 v[136:139], v79 offset:48
	s_waitcnt lgkmcnt(3)
	v_fmac_f32_e32 v129, v108, v100
	v_fmac_f32_e32 v125, v108, v101
	v_fmac_f32_e32 v124, v108, v102
	s_waitcnt lgkmcnt(1)
	v_fmac_f32_e32 v130, v108, v112
	v_fmac_f32_e32 v128, v108, v113
	v_cndmask_b32_e64 v100, v129, v130, s[26:27]
	v_fmac_f32_e32 v127, v108, v114
	ds_bpermute_b32 v100, v19, v100
	v_cndmask_b32_e64 v102, v125, v128, s[26:27]
	v_fmac_f32_e32 v123, v108, v103
	ds_bpermute_b32 v102, v19, v102
	v_cndmask_b32_e64 v103, v124, v127, s[26:27]
	ds_bpermute_b32 v103, v19, v103
	v_cndmask_b32_e64 v101, v130, v129, s[26:27]
	s_waitcnt lgkmcnt(2)
	v_add_f32_e32 v100, v101, v100
	v_cndmask_b32_e64 v101, v128, v125, s[26:27]
	v_fmac_f32_e32 v126, v108, v115
	s_waitcnt lgkmcnt(1)
	v_add_f32_e32 v101, v101, v102
	v_cndmask_b32_e64 v102, v127, v124, s[26:27]
	v_fmac_f32_e32 v119, v108, v104
	v_fmac_f32_e32 v122, v108, v136
	s_waitcnt lgkmcnt(0)
	v_add_f32_e32 v102, v102, v103
	v_cndmask_b32_e64 v103, v123, v126, s[26:27]
	v_fmac_f32_e32 v118, v108, v105
	v_fmac_f32_e32 v121, v108, v137
	ds_bpermute_b32 v103, v19, v103
	v_cndmask_b32_e64 v105, v119, v122, s[26:27]
	v_fmac_f32_e32 v117, v108, v106
	ds_bpermute_b32 v105, v19, v105
	v_cndmask_b32_e64 v106, v118, v121, s[26:27]
	ds_bpermute_b32 v106, v19, v106
	v_cndmask_b32_e64 v104, v126, v123, s[26:27]
	s_waitcnt lgkmcnt(2)
	v_add_f32_e32 v103, v104, v103
	v_cndmask_b32_e64 v104, v122, v119, s[26:27]
	v_fmac_f32_e32 v120, v108, v138
	s_waitcnt lgkmcnt(1)
	v_add_f32_e32 v104, v104, v105
	v_cndmask_b32_e64 v105, v121, v118, s[26:27]
	v_fmac_f32_e32 v111, v108, v107
	v_fmac_f32_e32 v116, v108, v139
	s_waitcnt lgkmcnt(0)
; __device__ __forceinline__ void p0_phase(const Args& a, LAS unsigned char* lds, int tid, int lane, int wave) {
;     ...
;                   for (int k = 0; k < 2; ++k) { const float send = b3 ? f[k] : f[k + 2], keep = b3 ? f[k + 2] : f[k]; f[k] = keep + __shfl_xor(send, 8); }
;                   const bool b2 = lane & 4;
;                   { const float send = b2 ? f[0] : f[1], keep = b2 ? f[1] : f[0]; f[0] = keep + __shfl_xor(send, 4); }
;                   f[0] += __shfl_xor(f[0], 2); f[0] += __shfl_xor(f[0], 1); }
;                 if ((lane & 3) == 0) { const int hh = ((lane >> 5) & 1) * 8 + ((lane >> 4) & 1) * 4 + ((lane >> 3) & 1) * 2 + ((lane >> 2) & 1);
;                     const float z = f[0] + bfg[hh]; const float lg = fminf(z, 0.f) - log1pf(expf(-fabsf(z)));
;                     lf[rl * 16 + hh] = lg;
;                     if (row < MP) a.out[O_LFP + (size_t)row * NH + hh] = lg; else a.out[O_LFS + (size_t)(row - MP) * NH + hh] = lg; }
	v_add_f32_e32 v105, v105, v106
	v_cndmask_b32_e64 v106, v117, v120, s[26:27]
	ds_bpermute_b32 v106, v19, v106
	v_cndmask_b32_e64 v108, v111, v116, s[26:27]
	ds_bpermute_b32 v108, v19, v108
	v_cndmask_b32_e64 v107, v120, v117, s[26:27]
	v_cndmask_b32_e64 v110, v100, v104, s[28:29]
	s_waitcnt lgkmcnt(1)
	v_add_f32_e32 v106, v107, v106
	v_cndmask_b32_e64 v107, v116, v111, s[26:27]
	s_waitcnt lgkmcnt(0)
	v_add_f32_e32 v107, v107, v108
	v_cndmask_b32_e64 v100, v104, v100, s[28:29]
	v_cndmask_b32_e64 v104, v101, v105, s[28:29]
	v_cndmask_b32_e64 v101, v105, v101, s[28:29]
	v_cndmask_b32_e64 v105, v102, v106, s[28:29]
	v_cndmask_b32_e64 v108, v103, v107, s[28:29]
	ds_bpermute_b32 v110, v18, v110
	ds_bpermute_b32 v104, v18, v104
	ds_bpermute_b32 v105, v18, v105
	ds_bpermute_b32 v108, v18, v108
	v_cndmask_b32_e64 v102, v106, v102, s[28:29]
	v_cndmask_b32_e64 v103, v107, v103, s[28:29]
	s_waitcnt lgkmcnt(3)
	v_add_f32_e32 v100, v100, v110
	s_waitcnt lgkmcnt(2)
	v_add_f32_e32 v101, v101, v104
	s_waitcnt lgkmcnt(1)
	v_add_f32_e32 v102, v102, v105
	s_waitcnt lgkmcnt(0)
	v_add_f32_e32 v103, v103, v108
	v_cndmask_b32_e64 v104, v100, v102, s[30:31]
	v_cndmask_b32_e64 v105, v101, v103, s[30:31]
	ds_bpermute_b32 v104, v17, v104
	ds_bpermute_b32 v105, v17, v105
	v_cndmask_b32_e64 v100, v102, v100, s[30:31]
	v_cndmask_b32_e64 v101, v103, v101, s[30:31]
	global_store_short v[0:1], v109, off offset:1920
	s_waitcnt lgkmcnt(1)
	v_add_f32_e32 v100, v100, v104
	s_waitcnt lgkmcnt(0)
	v_add_f32_e32 v101, v101, v105
	v_cndmask_b32_e64 v102, v100, v101, s[34:35]
	ds_bpermute_b32 v102, v4, v102
	v_cndmask_b32_e64 v100, v101, v100, s[34:35]
	s_waitcnt lgkmcnt(0)
	v_add_f32_e32 v100, v100, v102
	ds_bpermute_b32 v101, v3, v100
	s_waitcnt lgkmcnt(0)
	v_add_f32_e32 v100, v100, v101
	ds_bpermute_b32 v101, v2, v100
	s_and_saveexec_b64 s[0:1], s[36:37]
	s_cbranch_execz .LBB0_37
	global_load_dword v0, v[10:11], off
	s_waitcnt lgkmcnt(0)
	v_add_f32_e32 v1, v100, v101
	v_lshl_add_u32 v100, s11, 6, v51
	s_add_i32 s11, s92, 0xffffc000
	s_cmpk_lt_i32 s92, 0x4000
	s_cselect_b32 s13, s93, 0
	s_cselect_b32 s12, s92, s11
	s_cselect_b32 s11, s7, 0xcd04000
	s_lshl_b64 s[12:13], s[12:13], 6
	s_add_u32 s12, s86, s12
	s_addc_u32 s13, s87, s13
	s_add_u32 s92, s12, s11
	s_addc_u32 s93, s13, 0
	s_waitcnt vmcnt(0)
	v_add_f32_e32 v0, v1, v0
	v_mul_f32_e64 v1, |v0|, s70
	v_fma_f32 v101, |v0|, s70, -v1
	v_rndne_f32_e32 v102, v1
	v_fma_f32 v101, |v0|, s71, v101
	v_sub_f32_e32 v1, v1, v102
	v_add_f32_e32 v1, v1, v101
	v_cvt_i32_f32_e32 v102, v102
	v_exp_f32_e32 v1, v1
	v_cmp_ngt_f32_e64 vcc, |v0|, s50
	v_min_f32_e32 v101, 0, v0
	v_ldexp_f32 v1, v1, v102
	v_cndmask_b32_e32 v1, 0, v1, vcc
	v_cmp_nlt_f32_e64 vcc, |v0|, s94
	s_nop 1
	v_cndmask_b32_e32 v102, v63, v1, vcc
	v_add_f32_e32 v103, 1.0, v102
	v_add_f32_e32 v104, -1.0, v103
	v_frexp_mant_f32_e32 v105, v103
	v_cvt_f64_f32_e32 v[0:1], v103
	v_sub_f32_e32 v106, v104, v103
	v_frexp_exp_i32_f64_e32 v0, v[0:1]
	v_cmp_gt_f32_e32 vcc, s4, v105
	v_sub_f32_e32 v104, v102, v104
	v_add_f32_e32 v1, 1.0, v106
	v_subbrev_co_u32_e32 v0, vcc, 0, v0, vcc
	v_add_f32_e32 v1, v104, v1
	v_sub_u32_e32 v104, 0, v0
	v_cvt_f32_i32_e32 v0, v0
	v_ldexp_f32 v103, v103, v104
	v_ldexp_f32 v1, v1, v104
	v_add_f32_e32 v104, -1.0, v103
	v_add_f32_e32 v105, 1.0, v103
	v_add_f32_e32 v106, 1.0, v104
	v_add_f32_e32 v107, -1.0, v105
	v_sub_f32_e32 v106, v103, v106
	v_sub_f32_e32 v103, v103, v107
	v_mul_f32_e32 v107, 0x3f317218, v0
	v_add_f32_e32 v106, v1, v106
	v_add_f32_e32 v1, v1, v103
	v_fma_f32 v103, v0, s5, -v107
	v_add_f32_e32 v108, v104, v106
	v_add_f32_e32 v109, v105, v1
	v_fmac_f32_e32 v103, 0xb102e308, v0
	v_sub_f32_e32 v0, v104, v108
	v_sub_f32_e32 v104, v105, v109
	v_rcp_f32_e32 v105, v109
	v_add_f32_e32 v110, v107, v103
	v_add_f32_e32 v1, v1, v104
	v_sub_f32_e32 v104, v110, v107
	v_sub_f32_e32 v103, v103, v104
	v_mul_f32_e32 v104, v108, v105
	v_add_f32_e32 v0, v106, v0
	v_mul_f32_e32 v106, v109, v104
	v_fma_f32 v107, v104, v109, -v106
	v_fmac_f32_e32 v107, v104, v1
	v_add_f32_e32 v111, v106, v107
	v_sub_f32_e32 v112, v108, v111
	v_sub_f32_e32 v106, v111, v106
	v_sub_f32_e32 v108, v108, v112
	v_sub_f32_e32 v106, v106, v107
	v_sub_f32_e32 v107, v108, v111
	v_add_f32_e32 v0, v0, v107
	v_add_f32_e32 v0, v106, v0
	v_add_f32_e32 v106, v112, v0
	v_mul_f32_e32 v107, v105, v106
	v_sub_f32_e32 v108, v112, v106
	v_mul_f32_e32 v111, v109, v107
	v_add_f32_e32 v0, v0, v108
	v_add_f32_e32 v108, v104, v107
	v_fma_f32 v109, v107, v109, -v111
	v_sub_f32_e32 v104, v108, v104
	v_fmac_f32_e32 v109, v107, v1
	v_sub_f32_e32 v1, v107, v104
	v_add_f32_e32 v104, v111, v109
	v_sub_f32_e32 v107, v104, v111
	v_sub_f32_e32 v111, v106, v104
	v_sub_f32_e32 v106, v106, v111
	v_sub_f32_e32 v104, v106, v104
	v_sub_f32_e32 v107, v107, v109
	v_add_f32_e32 v0, v0, v104
	v_add_f32_e32 v0, v107, v0
	v_add_f32_e32 v0, v111, v0
	v_mul_f32_e32 v0, v105, v0
	v_add_f32_e32 v0, v1, v0
	v_add_f32_e32 v1, v108, v0
	v_mul_f32_e32 v104, v1, v1
	v_fmamk_f32 v107, v104, 0x3e9b6dac, v62
	v_sub_f32_e32 v105, v1, v108
	v_ldexp_f32 v106, v1, 1
	v_mul_f32_e32 v1, v1, v104
	v_fmaak_f32 v104, v104, v107, 0x3f2aaada
	v_mul_f32_e32 v1, v1, v104
	v_add_f32_e32 v104, v106, v1
	v_sub_f32_e32 v0, v0, v105
	v_sub_f32_e32 v105, v104, v106
	v_ldexp_f32 v0, v0, 1
	v_sub_f32_e32 v1, v1, v105
	v_add_f32_e32 v0, v0, v1
	v_add_f32_e32 v1, v104, v0
	v_sub_f32_e32 v104, v1, v104
	v_add_f32_e32 v105, v110, v1
	v_sub_f32_e32 v0, v0, v104
	v_sub_f32_e32 v104, v105, v110
	v_sub_f32_e32 v106, v105, v104
	v_sub_f32_e32 v1, v1, v104
	v_add_f32_e32 v104, v103, v0
	v_sub_f32_e32 v106, v110, v106
	v_sub_f32_e32 v107, v104, v103
	v_add_f32_e32 v1, v1, v106
	v_sub_f32_e32 v106, v104, v107
	v_sub_f32_e32 v0, v0, v107
	v_sub_f32_e32 v103, v103, v106
	v_add_f32_e32 v1, v104, v1
	v_add_f32_e32 v0, v0, v103
	v_add_f32_e32 v103, v105, v1
	v_sub_f32_e32 v104, v103, v105
	v_sub_f32_e32 v1, v1, v104
	v_add_f32_e32 v0, v0, v1
	v_add_f32_e32 v0, v103, v0
	v_cmp_neq_f32_e32 vcc, s95, v102
	s_nop 1
	v_cndmask_b32_e32 v0, v63, v0, vcc
	v_cmp_lt_f32_e64 vcc, |v102|, s6
	s_nop 1
	v_cndmask_b32_e32 v0, v0, v102, vcc
	v_sub_f32_e32 v0, v101, v0
	ds_write_b32 v100, v0
	global_store_dword v33, v0, s[92:93]
; #define LAS __attribute__((address_space(3)))
; __device__ __forceinline__ unsigned cvt_pk_bf16(float lo, float hi) { unsigned r; asm volatile("v_cvt_pk_bf16_f32 %0, %1, %2" : "=v"(r) : "v"(lo), "v"(hi)); return r; }
; __device__ __forceinline__ void p0_phase(const Args& a, LAS unsigned char* lds, int tid, int lane, int wave) {
;     ...
;                 for (int u = 0; u < 4; ++u) {
;                 const int rl = wave * 8 + i4 * 4 + u, row = c * 64 + rl;
;                 float ss = 0.f;
; #pragma unroll
;                 for (int j = 0; j < 16; ++j) ss += xa[u][j] * xa[u][j];
;                 const float rstd = 1.0f / sqrtf(wave_sum(ss) * (1.f / D) + EPS);
;                 float f[16];
; #pragma unroll
;                 for (int h = 0; h < 16; ++h) f[h] = 0.f;
; #pragma unroll
;                 for (int j = 0; j < 16; ++j) { const float xn = xa[u][j] * rstd * gm[j];
;                     XN[(size_t)row * D + lane + 64 * j] = (bf16_t)(cvt_pk_bf16(xn, 0.f) & 0xffffu);
;                     const LAS f32x4* wp = (const LAS f32x4*)(wfl + (lane + 64 * j) * 16);
; #pragma unroll
;                     for (int q = 0; q < 4; ++q) { const f32x4 w = wp[q]; f[4 * q + 0] += xn * w[0]; f[4 * q + 1] += xn * w[1]; f[4 * q + 2] += xn * w[2]; f[4 * q + 3] += xn * w[3]; } }
.LBB0_37:
	s_or_b64 exec, exec, s[0:1]
	s_waitcnt vmcnt(60)
	v_mul_f32_e32 v0, v98, v98
	v_fmac_f32_e32 v0, v99, v99
	s_waitcnt vmcnt(59)
	v_fmac_f32_e32 v0, v97, v97
	s_waitcnt vmcnt(58)
	v_fmac_f32_e32 v0, v96, v96
	s_waitcnt vmcnt(57)
	v_fmac_f32_e32 v0, v95, v95
	s_waitcnt vmcnt(56)
	v_fmac_f32_e32 v0, v94, v94
	s_waitcnt vmcnt(55)
	v_fmac_f32_e32 v0, v93, v93
	s_waitcnt vmcnt(54)
	v_fmac_f32_e32 v0, v92, v92
	s_waitcnt vmcnt(53)
	v_fmac_f32_e32 v0, v91, v91
	s_waitcnt vmcnt(52)
	v_fmac_f32_e32 v0, v90, v90
	s_waitcnt vmcnt(51)
	v_fmac_f32_e32 v0, v89, v89
	s_waitcnt vmcnt(50)
	v_fmac_f32_e32 v0, v88, v88
	s_waitcnt vmcnt(49)
	v_fmac_f32_e32 v0, v87, v87
	s_waitcnt vmcnt(48)
	v_fmac_f32_e32 v0, v86, v86
	s_waitcnt vmcnt(47)
	v_fmac_f32_e32 v0, v85, v85
	v_fmac_f32_e32 v0, v84, v84
	ds_bpermute_b32 v1, v2, v0
	s_or_b32 s11, s10, 2
	s_add_i32 s92, s11, s45
	s_ashr_i32 s93, s92, 31
	s_lshl_b64 s[12:13], s[92:93], 11
	s_waitcnt lgkmcnt(0)
	v_add_f32_e32 v0, v0, v1
	ds_bpermute_b32 v1, v3, v0
	s_waitcnt lgkmcnt(0)
	v_add_f32_e32 v0, v0, v1
	ds_bpermute_b32 v1, v4, v0
	s_waitcnt lgkmcnt(0)
	v_add_f32_e32 v0, v0, v1
	ds_bpermute_b32 v1, v17, v0
	s_waitcnt lgkmcnt(0)
	v_add_f32_e32 v0, v0, v1
	ds_bpermute_b32 v1, v18, v0
	s_waitcnt lgkmcnt(0)
	v_add_f32_e32 v0, v0, v1
	ds_bpermute_b32 v1, v19, v0
	s_waitcnt lgkmcnt(0)
	v_add_f32_e32 v0, v0, v1
	v_fmamk_f32 v0, v0, 0x3a800000, v60
	v_mul_f32_e32 v1, 0x4f800000, v0
	v_cmp_gt_f32_e32 vcc, s49, v0
	s_nop 1
	v_cndmask_b32_e32 v0, v0, v1, vcc
	v_sqrt_f32_e32 v1, v0
	s_nop 0
	v_add_u32_e32 v100, -1, v1
	v_add_u32_e32 v101, 1, v1
	v_fma_f32 v102, -v100, v1, v0
	v_fma_f32 v103, -v101, v1, v0
	v_cmp_ge_f32_e64 s[0:1], 0, v102
	s_nop 1
	v_cndmask_b32_e64 v1, v1, v100, s[0:1]
	v_cmp_lt_f32_e64 s[0:1], 0, v103
	s_nop 1
	v_cndmask_b32_e64 v1, v1, v101, s[0:1]
	v_mul_f32_e32 v100, 0x37800000, v1
	v_cndmask_b32_e32 v1, v1, v100, vcc
	v_cmp_class_f32_e32 vcc, v0, v61
	s_nop 1
	v_cndmask_b32_e32 v100, v1, v0, vcc
	v_div_scale_f32 v101, s[0:1], v100, v100, 1.0
	v_rcp_f32_e32 v102, v101
	v_div_scale_f32 v103, vcc, 1.0, v100, 1.0
	v_lshl_add_u64 v[0:1], v[6:7], 0, s[12:13]
	v_fma_f32 v104, -v101, v102, 1.0
	v_fmac_f32_e32 v102, v104, v102
	v_mul_f32_e32 v104, v103, v102
	v_fma_f32 v105, -v101, v104, v103
	v_fmac_f32_e32 v104, v105, v102
	v_fma_f32 v101, -v101, v104, v103
	v_div_fmas_f32 v101, v101, v102, v104
	v_div_fixup_f32 v115, v101, v100, 1.0
	v_mul_f32_e32 v99, v99, v115
	v_mul_f32_e32 v128, v9, v99
	v_cvt_pk_bf16_f32 v99, v128, v5
	v_mul_f32_e32 v98, v98, v115
	global_store_short v[0:1], v99, off
	v_mul_f32_e32 v98, v34, v98
	s_waitcnt lgkmcnt(0)
	v_fma_f32 v114, v168, v128, 0
	v_cvt_pk_bf16_f32 v120, v98, v5
	global_store_short v[0:1], v120, off offset:128
	v_fma_f32 v113, v160, v128, 0
	v_fma_f32 v109, v161, v128, 0
	v_fma_f32 v108, v162, v128, 0
	v_fma_f32 v107, v163, v128, 0
	v_fma_f32 v103, v164, v128, 0
	v_fma_f32 v102, v165, v128, 0
	v_fma_f32 v101, v166, v128, 0
	v_fma_f32 v99, v167, v128, 0
	v_fma_f32 v112, v169, v128, 0
	v_fma_f32 v111, v170, v128, 0
	v_fma_f32 v110, v171, v128, 0
	s_waitcnt lgkmcnt(0)
	v_fma_f32 v106, v128, v172, 0
	v_fma_f32 v105, v128, v173, 0
	v_fma_f32 v104, v128, v174, 0
	v_fma_f32 v100, v128, v175, 0
	v_mul_f32_e32 v97, v97, v115
	v_mul_f32_e32 v97, v35, v97
	s_waitcnt lgkmcnt(0)
	v_fmac_f32_e32 v103, v98, v180
	v_fmac_f32_e32 v113, v98, v176
	v_fmac_f32_e32 v109, v98, v177
	v_fmac_f32_e32 v108, v98, v178
	v_fmac_f32_e32 v107, v98, v179
	v_fmac_f32_e32 v102, v98, v181
	v_fmac_f32_e32 v101, v98, v182
	v_fmac_f32_e32 v99, v98, v183
	s_waitcnt lgkmcnt(0)
	v_fmac_f32_e32 v114, v98, v184
	v_fmac_f32_e32 v112, v98, v185
	v_fmac_f32_e32 v111, v98, v186
	v_fmac_f32_e32 v110, v98, v187
	s_waitcnt lgkmcnt(0)
	v_fmac_f32_e32 v106, v98, v188
	v_fmac_f32_e32 v105, v98, v189
	v_fmac_f32_e32 v104, v98, v190
	v_fmac_f32_e32 v100, v98, v191
	v_cvt_pk_bf16_f32 v98, v97, v5
	global_store_short v[0:1], v98, off offset:256
	v_mul_f32_e32 v96, v96, v115
	v_mul_f32_e32 v96, v36, v96
	s_waitcnt lgkmcnt(0)
	v_fmac_f32_e32 v103, v97, v196
	v_fmac_f32_e32 v113, v97, v192
	v_fmac_f32_e32 v109, v97, v193
	v_fmac_f32_e32 v108, v97, v194
	v_fmac_f32_e32 v107, v97, v195
	v_fmac_f32_e32 v102, v97, v197
	v_fmac_f32_e32 v101, v97, v198
	v_fmac_f32_e32 v99, v97, v199
	s_waitcnt lgkmcnt(0)
	v_fmac_f32_e32 v114, v97, v200
	v_fmac_f32_e32 v112, v97, v201
	v_fmac_f32_e32 v111, v97, v202
	v_fmac_f32_e32 v110, v97, v203
	s_waitcnt lgkmcnt(0)
	v_fmac_f32_e32 v106, v97, v204
	v_fmac_f32_e32 v105, v97, v205
	v_fmac_f32_e32 v104, v97, v206
	v_fmac_f32_e32 v100, v97, v207
	v_cvt_pk_bf16_f32 v97, v96, v5
	global_store_short v[0:1], v97, off offset:384
	v_mul_f32_e32 v95, v95, v115
	v_mul_f32_e32 v95, v37, v95
	s_waitcnt lgkmcnt(0)
	v_fmac_f32_e32 v103, v96, v212
	v_fmac_f32_e32 v113, v96, v208
	v_fmac_f32_e32 v109, v96, v209
	v_fmac_f32_e32 v108, v96, v210
	v_fmac_f32_e32 v107, v96, v211
	v_fmac_f32_e32 v102, v96, v213
	v_fmac_f32_e32 v101, v96, v214
	v_fmac_f32_e32 v99, v96, v215
	s_waitcnt lgkmcnt(0)
	v_fmac_f32_e32 v114, v96, v216
	v_fmac_f32_e32 v112, v96, v217
	v_fmac_f32_e32 v111, v96, v218
	v_fmac_f32_e32 v110, v96, v219
	s_waitcnt lgkmcnt(0)
	v_fmac_f32_e32 v106, v96, v220
	v_fmac_f32_e32 v105, v96, v221
	v_fmac_f32_e32 v104, v96, v222
	v_fmac_f32_e32 v100, v96, v223
	v_cvt_pk_bf16_f32 v96, v95, v5
	global_store_short v[0:1], v96, off offset:512
	v_mul_f32_e32 v94, v94, v115
	v_mul_f32_e32 v98, v38, v94
	s_waitcnt lgkmcnt(0)
	v_fmac_f32_e32 v113, v95, v224
	v_cvt_pk_bf16_f32 v116, v98, v5
	global_store_short v[0:1], v116, off offset:640
	v_fmac_f32_e32 v109, v95, v225
	v_fmac_f32_e32 v108, v95, v226
	v_fmac_f32_e32 v107, v95, v227
	s_waitcnt lgkmcnt(0)
; #define LAS __attribute__((address_space(3)))
; __device__ __forceinline__ unsigned cvt_pk_bf16(float lo, float hi) { unsigned r; asm volatile("v_cvt_pk_bf16_f32 %0, %1, %2" : "=v"(r) : "v"(lo), "v"(hi)); return r; }
; __device__ __forceinline__ void p0_phase(const Args& a, LAS unsigned char* lds, int tid, int lane, int wave) {
;     ...
;                 for (int j = 0; j < 16; ++j) { const float xn = xa[u][j] * rstd * gm[j];
;                     XN[(size_t)row * D + lane + 64 * j] = (bf16_t)(cvt_pk_bf16(xn, 0.f) & 0xffffu);
;                     const LAS f32x4* wp = (const LAS f32x4*)(wfl + (lane + 64 * j) * 16);
; #pragma unroll
;                     for (int q = 0; q < 4; ++q) { const f32x4 w = wp[q]; f[4 * q + 0] += xn * w[0]; f[4 * q + 1] += xn * w[1]; f[4 * q + 2] += xn * w[2]; f[4 * q + 3] += xn * w[3]; } }
	v_fmac_f32_e32 v103, v95, v228
	v_fmac_f32_e32 v102, v95, v229
	v_fmac_f32_e32 v101, v95, v230
	v_fmac_f32_e32 v99, v95, v231
	s_waitcnt lgkmcnt(0)
	v_fmac_f32_e32 v114, v95, v232
	v_fmac_f32_e32 v112, v95, v233
	v_fmac_f32_e32 v111, v95, v234
	v_fmac_f32_e32 v110, v95, v235
	s_waitcnt lgkmcnt(0)
	v_fmac_f32_e32 v106, v95, v236
	v_fmac_f32_e32 v105, v95, v237
	v_fmac_f32_e32 v104, v95, v238
	v_fmac_f32_e32 v100, v95, v239
	ds_read_b128 v[124:127], v69 offset:48
	v_mul_f32_e32 v93, v93, v115
	v_mul_f32_e32 v93, v39, v93
	s_waitcnt lgkmcnt(1)
	v_fmac_f32_e32 v103, v98, v244
	v_fmac_f32_e32 v113, v98, v240
	v_fmac_f32_e32 v109, v98, v241
	v_fmac_f32_e32 v108, v98, v242
	v_fmac_f32_e32 v107, v98, v243
	v_fmac_f32_e32 v102, v98, v245
	v_fmac_f32_e32 v101, v98, v246
	v_fmac_f32_e32 v99, v98, v247
	s_waitcnt lgkmcnt(1)
	v_fmac_f32_e32 v114, v98, v248
	v_fmac_f32_e32 v112, v98, v249
	v_fmac_f32_e32 v111, v98, v250
	v_fmac_f32_e32 v110, v98, v251
	s_waitcnt lgkmcnt(0)
	v_fmac_f32_e32 v106, v98, v124
	v_fmac_f32_e32 v105, v98, v125
	v_fmac_f32_e32 v104, v98, v126
	v_fmac_f32_e32 v100, v98, v127
	v_cvt_pk_bf16_f32 v98, v93, v5
	ds_read_b128 v[94:97], v70
	global_store_short v[0:1], v98, off offset:768
	ds_read_b128 v[116:119], v70 offset:16
	ds_read_b128 v[120:123], v70 offset:32
	ds_read_b128 v[124:127], v70 offset:48
	v_mul_f32_e32 v92, v92, v115
	v_mul_f32_e32 v91, v91, v115
	s_waitcnt lgkmcnt(3)
	v_fmac_f32_e32 v108, v93, v96
	v_fmac_f32_e32 v107, v93, v97
	v_mul_f32_e32 v96, v40, v92
	v_cvt_pk_bf16_f32 v97, v96, v5
	global_store_short v[0:1], v97, off offset:896
	v_fmac_f32_e32 v113, v93, v94
	v_fmac_f32_e32 v109, v93, v95
	s_waitcnt lgkmcnt(2)
	v_fmac_f32_e32 v103, v93, v116
	v_fmac_f32_e32 v102, v93, v117
	v_fmac_f32_e32 v101, v93, v118
	v_fmac_f32_e32 v99, v93, v119
	s_waitcnt lgkmcnt(1)
	v_fmac_f32_e32 v114, v93, v120
	v_fmac_f32_e32 v112, v93, v121
	v_fmac_f32_e32 v111, v93, v122
	v_fmac_f32_e32 v110, v93, v123
	s_waitcnt lgkmcnt(0)
	v_fmac_f32_e32 v106, v93, v124
	v_fmac_f32_e32 v105, v93, v125
	v_fmac_f32_e32 v104, v93, v126
	v_fmac_f32_e32 v100, v93, v127
	ds_read_b128 v[92:95], v71
	ds_read_b128 v[116:119], v71 offset:16
	ds_read_b128 v[120:123], v71 offset:32
	ds_read_b128 v[124:127], v71 offset:48
	v_mul_f32_e32 v91, v41, v91
	v_mul_f32_e32 v90, v90, v115
	s_waitcnt lgkmcnt(2)
	v_fmac_f32_e32 v103, v96, v116
	v_fmac_f32_e32 v113, v96, v92
	v_fmac_f32_e32 v109, v96, v93
	v_fmac_f32_e32 v108, v96, v94
	v_fmac_f32_e32 v107, v96, v95
	v_fmac_f32_e32 v102, v96, v117
	v_fmac_f32_e32 v101, v96, v118
	v_fmac_f32_e32 v99, v96, v119
	s_waitcnt lgkmcnt(1)
	v_fmac_f32_e32 v114, v96, v120
	v_fmac_f32_e32 v112, v96, v121
	v_fmac_f32_e32 v111, v96, v122
	v_fmac_f32_e32 v110, v96, v123
	s_waitcnt lgkmcnt(0)
	v_fmac_f32_e32 v106, v96, v124
	v_fmac_f32_e32 v105, v96, v125
	v_fmac_f32_e32 v104, v96, v126
	v_fmac_f32_e32 v100, v96, v127
	v_cvt_pk_bf16_f32 v96, v91, v5
	ds_read_b128 v[92:95], v72
	global_store_short v[0:1], v96, off offset:1024
	ds_read_b128 v[116:119], v72 offset:16
	ds_read_b128 v[120:123], v72 offset:32
	ds_read_b128 v[124:127], v72 offset:48
	v_mul_f32_e32 v98, v42, v90
	v_mul_f32_e32 v89, v89, v115
	s_waitcnt lgkmcnt(3)
	v_fmac_f32_e32 v108, v91, v94
	v_cvt_pk_bf16_f32 v94, v98, v5
	global_store_short v[0:1], v94, off offset:1152
	v_fmac_f32_e32 v113, v91, v92
	v_fmac_f32_e32 v109, v91, v93
	v_fmac_f32_e32 v107, v91, v95
	s_waitcnt lgkmcnt(2)
	v_fmac_f32_e32 v103, v91, v116
	v_fmac_f32_e32 v102, v91, v117
	v_fmac_f32_e32 v101, v91, v118
	v_fmac_f32_e32 v99, v91, v119
	s_waitcnt lgkmcnt(1)
	v_fmac_f32_e32 v114, v91, v120
	v_fmac_f32_e32 v112, v91, v121
	v_fmac_f32_e32 v111, v91, v122
	v_fmac_f32_e32 v110, v91, v123
	s_waitcnt lgkmcnt(0)
	v_fmac_f32_e32 v106, v91, v124
	v_fmac_f32_e32 v105, v91, v125
	v_fmac_f32_e32 v104, v91, v126
	v_fmac_f32_e32 v100, v91, v127
	ds_read_b128 v[90:93], v73
	ds_read_b128 v[94:97], v73 offset:16
	ds_read_b128 v[116:119], v73 offset:32
	ds_read_b128 v[120:123], v73 offset:48
	v_mul_f32_e32 v89, v43, v89
	v_mul_f32_e32 v88, v88, v115
	s_waitcnt lgkmcnt(2)
	v_fmac_f32_e32 v103, v98, v94
	v_cvt_pk_bf16_f32 v94, v89, v5
	global_store_short v[0:1], v94, off offset:1280
	v_fmac_f32_e32 v113, v98, v90
	v_fmac_f32_e32 v109, v98, v91
	v_fmac_f32_e32 v108, v98, v92
	v_fmac_f32_e32 v107, v98, v93
	v_fmac_f32_e32 v102, v98, v95
	v_fmac_f32_e32 v101, v98, v96
	v_fmac_f32_e32 v99, v98, v97
	s_waitcnt lgkmcnt(1)
	v_fmac_f32_e32 v114, v98, v116
	v_fmac_f32_e32 v112, v98, v117
	v_fmac_f32_e32 v111, v98, v118
	v_fmac_f32_e32 v110, v98, v119
	s_waitcnt lgkmcnt(0)
	v_fmac_f32_e32 v106, v98, v120
	v_fmac_f32_e32 v105, v98, v121
	v_fmac_f32_e32 v104, v98, v122
	v_fmac_f32_e32 v100, v98, v123
	ds_read_b128 v[90:93], v74
	ds_read_b128 v[94:97], v74 offset:16
	ds_read_b128 v[116:119], v74 offset:32
	ds_read_b128 v[120:123], v74 offset:48
	v_mul_f32_e32 v87, v87, v115
	v_mul_f32_e32 v87, v45, v87
	s_waitcnt lgkmcnt(2)
	v_fmac_f32_e32 v103, v89, v94
	v_fmac_f32_e32 v113, v89, v90
	v_fmac_f32_e32 v109, v89, v91
	v_fmac_f32_e32 v108, v89, v92
	v_fmac_f32_e32 v107, v89, v93
	v_fmac_f32_e32 v102, v89, v95
	v_fmac_f32_e32 v101, v89, v96
	v_fmac_f32_e32 v99, v89, v97
	s_waitcnt lgkmcnt(1)
	v_fmac_f32_e32 v114, v89, v116
	v_fmac_f32_e32 v112, v89, v117
	v_fmac_f32_e32 v111, v89, v118
	v_fmac_f32_e32 v110, v89, v119
	s_waitcnt lgkmcnt(0)
	v_fmac_f32_e32 v106, v89, v120
	v_fmac_f32_e32 v105, v89, v121
	v_fmac_f32_e32 v104, v89, v122
	v_fmac_f32_e32 v100, v89, v123
	v_mul_f32_e32 v96, v44, v88
	v_cvt_pk_bf16_f32 v92, v96, v5
	ds_read_b128 v[88:91], v75
	global_store_short v[0:1], v92, off offset:1408
	ds_read_b128 v[92:95], v75 offset:16
	ds_read_b128 v[116:119], v75 offset:32
	ds_read_b128 v[120:123], v75 offset:48
	v_mul_f32_e32 v86, v86, v115
	v_mul_f32_e32 v98, v46, v86
	s_waitcnt lgkmcnt(3)
; #define LAS __attribute__((address_space(3)))
; __device__ __forceinline__ unsigned cvt_pk_bf16(float lo, float hi) { unsigned r; asm volatile("v_cvt_pk_bf16_f32 %0, %1, %2" : "=v"(r) : "v"(lo), "v"(hi)); return r; }
; __device__ __forceinline__ void p0_phase(const Args& a, LAS unsigned char* lds, int tid, int lane, int wave) {
;     ...
;                 for (int j = 0; j < 16; ++j) { const float xn = xa[u][j] * rstd * gm[j];
;                     XN[(size_t)row * D + lane + 64 * j] = (bf16_t)(cvt_pk_bf16(xn, 0.f) & 0xffffu);
;                     const LAS f32x4* wp = (const LAS f32x4*)(wfl + (lane + 64 * j) * 16);
; #pragma unroll
;                     for (int q = 0; q < 4; ++q) { const f32x4 w = wp[q]; f[4 * q + 0] += xn * w[0]; f[4 * q + 1] += xn * w[1]; f[4 * q + 2] += xn * w[2]; f[4 * q + 3] += xn * w[3]; } }
;                 { const bool b5 = lane & 32;
; #pragma unroll
;                   for (int k = 0; k < 8; ++k) { const float send = b5 ? f[k] : f[k + 8], keep = b5 ? f[k + 8] : f[k]; f[k] = keep + __shfl_xor(send, 32); }
;                   const bool b4 = lane & 16;
; #pragma unroll
;                   for (int k = 0; k < 4; ++k) { const float send = b4 ? f[k] : f[k + 4], keep = b4 ? f[k + 4] : f[k]; f[k] = keep + __shfl_xor(send, 16); }
;                   const bool b3 = lane & 8;
; #pragma unroll
;                   for (int k = 0; k < 2; ++k) { const float send = b3 ? f[k] : f[k + 2], keep = b3 ? f[k + 2] : f[k]; f[k] = keep + __shfl_xor(send, 8); }
;                   const bool b2 = lane & 4;
;                   { const float send = b2 ? f[0] : f[1], keep = b2 ? f[1] : f[0]; f[0] = keep + __shfl_xor(send, 4); }
;                   f[0] += __shfl_xor(f[0], 2); f[0] += __shfl_xor(f[0], 1); }
;                 if ((lane & 3) == 0) { const int hh = ((lane >> 5) & 1) * 8 + ((lane >> 4) & 1) * 4 + ((lane >> 3) & 1) * 2 + ((lane >> 2) & 1);
	v_fmac_f32_e32 v113, v96, v88
	v_fmac_f32_e32 v109, v96, v89
	v_fmac_f32_e32 v108, v96, v90
	v_fmac_f32_e32 v107, v96, v91
	s_waitcnt lgkmcnt(2)
	v_fmac_f32_e32 v103, v96, v92
	v_cvt_pk_bf16_f32 v92, v87, v5
	ds_read_b128 v[88:91], v76
	global_store_short v[0:1], v92, off offset:1536
	v_fmac_f32_e32 v102, v96, v93
	v_fmac_f32_e32 v101, v96, v94
	v_fmac_f32_e32 v99, v96, v95
	s_waitcnt lgkmcnt(2)
	v_fmac_f32_e32 v114, v96, v116
	v_fmac_f32_e32 v112, v96, v117
	v_fmac_f32_e32 v111, v96, v118
	v_fmac_f32_e32 v110, v96, v119
	s_waitcnt lgkmcnt(1)
	v_fmac_f32_e32 v106, v96, v120
	v_fmac_f32_e32 v105, v96, v121
	v_fmac_f32_e32 v104, v96, v122
	v_fmac_f32_e32 v100, v96, v123
	ds_read_b128 v[92:95], v76 offset:16
	ds_read_b128 v[116:119], v76 offset:32
	ds_read_b128 v[120:123], v76 offset:48
	s_waitcnt lgkmcnt(3)
	v_fmac_f32_e32 v108, v87, v90
	v_cvt_pk_bf16_f32 v90, v98, v5
	global_store_short v[0:1], v90, off offset:1664
	v_fmac_f32_e32 v113, v87, v88
	v_fmac_f32_e32 v109, v87, v89
	v_fmac_f32_e32 v107, v87, v91
	s_waitcnt lgkmcnt(2)
	v_fmac_f32_e32 v103, v87, v92
	v_fmac_f32_e32 v102, v87, v93
	v_fmac_f32_e32 v101, v87, v94
	v_fmac_f32_e32 v99, v87, v95
	s_waitcnt lgkmcnt(1)
	v_fmac_f32_e32 v114, v87, v116
	v_fmac_f32_e32 v112, v87, v117
	v_fmac_f32_e32 v111, v87, v118
	v_fmac_f32_e32 v110, v87, v119
	s_waitcnt lgkmcnt(0)
	v_fmac_f32_e32 v106, v87, v120
	v_fmac_f32_e32 v105, v87, v121
	v_fmac_f32_e32 v104, v87, v122
	v_fmac_f32_e32 v100, v87, v123
	ds_read_b128 v[86:89], v77
	ds_read_b128 v[90:93], v77 offset:16
	ds_read_b128 v[94:97], v77 offset:32
	ds_read_b128 v[116:119], v77 offset:48
	v_mul_f32_e32 v85, v85, v115
	v_mul_f32_e32 v84, v84, v115
	s_waitcnt lgkmcnt(2)
	v_fmac_f32_e32 v103, v98, v90
	v_fmac_f32_e32 v113, v98, v86
	v_fmac_f32_e32 v109, v98, v87
	v_fmac_f32_e32 v108, v98, v88
	v_fmac_f32_e32 v107, v98, v89
	v_fmac_f32_e32 v102, v98, v91
	v_fmac_f32_e32 v101, v98, v92
	v_fmac_f32_e32 v99, v98, v93
	s_waitcnt lgkmcnt(1)
	v_fmac_f32_e32 v114, v98, v94
	v_fmac_f32_e32 v112, v98, v95
	v_fmac_f32_e32 v111, v98, v96
	v_fmac_f32_e32 v110, v98, v97
	s_waitcnt lgkmcnt(0)
	v_fmac_f32_e32 v106, v98, v116
	v_fmac_f32_e32 v105, v98, v117
	v_fmac_f32_e32 v104, v98, v118
	v_fmac_f32_e32 v100, v98, v119
	v_mul_f32_e32 v98, v47, v85
	v_cvt_pk_bf16_f32 v85, v98, v5
	ds_read_b128 v[86:89], v78
	global_store_short v[0:1], v85, off offset:1792
	ds_read_b128 v[90:93], v78 offset:16
	ds_read_b128 v[94:97], v78 offset:32
	ds_read_b128 v[116:119], v78 offset:48
	s_waitcnt lgkmcnt(3)
	v_fmac_f32_e32 v113, v98, v86
	v_fmac_f32_e32 v109, v98, v87
	s_waitcnt lgkmcnt(1)
	v_fmac_f32_e32 v111, v98, v96
	v_fmac_f32_e32 v110, v98, v97
	v_mul_f32_e32 v96, v48, v84
	v_cvt_pk_bf16_f32 v97, v96, v5
	ds_read_b128 v[84:87], v79
	v_fmac_f32_e32 v108, v98, v88
	v_fmac_f32_e32 v107, v98, v89
	v_fmac_f32_e32 v103, v98, v90
	v_fmac_f32_e32 v102, v98, v91
	v_fmac_f32_e32 v101, v98, v92
	v_fmac_f32_e32 v99, v98, v93
	v_fmac_f32_e32 v114, v98, v94
	v_fmac_f32_e32 v112, v98, v95
	s_waitcnt lgkmcnt(1)
	v_fmac_f32_e32 v106, v98, v116
	v_fmac_f32_e32 v105, v98, v117
	v_fmac_f32_e32 v104, v98, v118
	v_fmac_f32_e32 v100, v98, v119
	ds_read_b128 v[88:91], v79 offset:16
	ds_read_b128 v[92:95], v79 offset:32
	ds_read_b128 v[116:119], v79 offset:48
	s_waitcnt lgkmcnt(3)
	v_fmac_f32_e32 v113, v96, v84
	v_fmac_f32_e32 v109, v96, v85
	v_fmac_f32_e32 v108, v96, v86
	s_waitcnt lgkmcnt(1)
	v_fmac_f32_e32 v114, v96, v92
	v_fmac_f32_e32 v112, v96, v93
	v_cndmask_b32_e64 v84, v113, v114, s[26:27]
	v_fmac_f32_e32 v111, v96, v94
	ds_bpermute_b32 v84, v19, v84
	v_cndmask_b32_e64 v86, v109, v112, s[26:27]
	v_fmac_f32_e32 v107, v96, v87
	ds_bpermute_b32 v86, v19, v86
	v_cndmask_b32_e64 v87, v108, v111, s[26:27]
	ds_bpermute_b32 v87, v19, v87
	v_cndmask_b32_e64 v85, v114, v113, s[26:27]
	s_waitcnt lgkmcnt(2)
	v_add_f32_e32 v84, v85, v84
	v_cndmask_b32_e64 v85, v112, v109, s[26:27]
	v_fmac_f32_e32 v110, v96, v95
	s_waitcnt lgkmcnt(1)
	v_add_f32_e32 v85, v85, v86
	v_cndmask_b32_e64 v86, v111, v108, s[26:27]
	v_fmac_f32_e32 v103, v96, v88
	v_fmac_f32_e32 v106, v96, v116
	s_waitcnt lgkmcnt(0)
	v_add_f32_e32 v86, v86, v87
	v_cndmask_b32_e64 v87, v107, v110, s[26:27]
	v_fmac_f32_e32 v102, v96, v89
	v_fmac_f32_e32 v105, v96, v117
	ds_bpermute_b32 v87, v19, v87
	v_cndmask_b32_e64 v89, v103, v106, s[26:27]
	v_fmac_f32_e32 v101, v96, v90
	ds_bpermute_b32 v89, v19, v89
	v_cndmask_b32_e64 v90, v102, v105, s[26:27]
	ds_bpermute_b32 v90, v19, v90
	v_cndmask_b32_e64 v88, v110, v107, s[26:27]
	s_waitcnt lgkmcnt(2)
	v_add_f32_e32 v87, v88, v87
	v_cndmask_b32_e64 v88, v106, v103, s[26:27]
	v_fmac_f32_e32 v104, v96, v118
	s_waitcnt lgkmcnt(1)
	v_add_f32_e32 v88, v88, v89
	v_cndmask_b32_e64 v89, v105, v102, s[26:27]
	v_fmac_f32_e32 v99, v96, v91
	v_fmac_f32_e32 v100, v96, v119
	s_waitcnt lgkmcnt(0)
	v_add_f32_e32 v89, v89, v90
	v_cndmask_b32_e64 v90, v101, v104, s[26:27]
	ds_bpermute_b32 v90, v19, v90
	v_cndmask_b32_e64 v92, v99, v100, s[26:27]
	ds_bpermute_b32 v92, v19, v92
	v_cndmask_b32_e64 v91, v104, v101, s[26:27]
	v_cndmask_b32_e64 v93, v84, v88, s[28:29]
	s_waitcnt lgkmcnt(1)
	v_add_f32_e32 v90, v91, v90
	v_cndmask_b32_e64 v91, v100, v99, s[26:27]
	s_waitcnt lgkmcnt(0)
	v_add_f32_e32 v91, v91, v92
	v_cndmask_b32_e64 v84, v88, v84, s[28:29]
	v_cndmask_b32_e64 v88, v85, v89, s[28:29]
	v_cndmask_b32_e64 v85, v89, v85, s[28:29]
	v_cndmask_b32_e64 v89, v86, v90, s[28:29]
	v_cndmask_b32_e64 v92, v87, v91, s[28:29]
	ds_bpermute_b32 v93, v18, v93
	ds_bpermute_b32 v88, v18, v88
	ds_bpermute_b32 v89, v18, v89
	ds_bpermute_b32 v92, v18, v92
	v_cndmask_b32_e64 v86, v90, v86, s[28:29]
	v_cndmask_b32_e64 v87, v91, v87, s[28:29]
	s_waitcnt lgkmcnt(3)
	v_add_f32_e32 v84, v84, v93
	s_waitcnt lgkmcnt(2)
	v_add_f32_e32 v85, v85, v88
	s_waitcnt lgkmcnt(1)
	v_add_f32_e32 v86, v86, v89
	s_waitcnt lgkmcnt(0)
	v_add_f32_e32 v87, v87, v92
	v_cndmask_b32_e64 v88, v84, v86, s[30:31]
	v_cndmask_b32_e64 v89, v85, v87, s[30:31]
	ds_bpermute_b32 v88, v17, v88
	ds_bpermute_b32 v89, v17, v89
	v_cndmask_b32_e64 v84, v86, v84, s[30:31]
	v_cndmask_b32_e64 v85, v87, v85, s[30:31]
	global_store_short v[0:1], v97, off offset:1920
	s_waitcnt lgkmcnt(1)
	v_add_f32_e32 v84, v84, v88
	s_waitcnt lgkmcnt(0)
	v_add_f32_e32 v85, v85, v89
	v_cndmask_b32_e64 v86, v84, v85, s[34:35]
	ds_bpermute_b32 v86, v4, v86
	v_cndmask_b32_e64 v84, v85, v84, s[34:35]
	s_waitcnt lgkmcnt(0)
	v_add_f32_e32 v84, v84, v86
	ds_bpermute_b32 v85, v3, v84
	s_waitcnt lgkmcnt(0)
	v_add_f32_e32 v84, v84, v85
	ds_bpermute_b32 v85, v2, v84
	s_and_saveexec_b64 s[0:1], s[36:37]
	s_cbranch_execz .LBB0_39
; __device__ __forceinline__ void p0_phase(const Args& a, LAS unsigned char* lds, int tid, int lane, int wave) {
;     ...
;                 for (int u = 0; u < 4; ++u) {
;                 const int rl = wave * 8 + i4 * 4 + u, row = c * 64 + rl;
;                 float ss = 0.f;
; #pragma unroll
;                 for (int j = 0; j < 16; ++j) ss += xa[u][j] * xa[u][j];
;                 const float rstd = 1.0f / sqrtf(wave_sum(ss) * (1.f / D) + EPS);
;     ...
;                 if ((lane & 3) == 0) { const int hh = ((lane >> 5) & 1) * 8 + ((lane >> 4) & 1) * 4 + ((lane >> 3) & 1) * 2 + ((lane >> 2) & 1);
;                     const float z = f[0] + bfg[hh]; const float lg = fminf(z, 0.f) - log1pf(expf(-fabsf(z)));
;                     lf[rl * 16 + hh] = lg;
;                     if (row < MP) a.out[O_LFP + (size_t)row * NH + hh] = lg; else a.out[O_LFS + (size_t)(row - MP) * NH + hh] = lg; }
	global_load_dword v0, v[10:11], off
	s_waitcnt lgkmcnt(0)
	v_add_f32_e32 v1, v84, v85
	v_lshl_add_u32 v84, s11, 6, v51
	s_add_i32 s11, s92, 0xffffc000
	s_cmpk_lt_i32 s92, 0x4000
	s_cselect_b32 s13, s93, 0
	s_cselect_b32 s12, s92, s11
	s_cselect_b32 s11, s7, 0xcd04000
	s_lshl_b64 s[12:13], s[12:13], 6
	s_add_u32 s12, s86, s12
	s_addc_u32 s13, s87, s13
	s_add_u32 s92, s12, s11
	s_addc_u32 s93, s13, 0
	s_waitcnt vmcnt(0)
	v_add_f32_e32 v0, v1, v0
	v_mul_f32_e64 v1, |v0|, s70
	v_fma_f32 v85, |v0|, s70, -v1
	v_rndne_f32_e32 v86, v1
	v_fma_f32 v85, |v0|, s71, v85
	v_sub_f32_e32 v1, v1, v86
	v_add_f32_e32 v1, v1, v85
	v_cvt_i32_f32_e32 v86, v86
	v_exp_f32_e32 v1, v1
	v_cmp_ngt_f32_e64 vcc, |v0|, s50
	v_min_f32_e32 v85, 0, v0
	v_ldexp_f32 v1, v1, v86
	v_cndmask_b32_e32 v1, 0, v1, vcc
	v_cmp_nlt_f32_e64 vcc, |v0|, s94
	s_nop 1
	v_cndmask_b32_e32 v86, v63, v1, vcc
	v_add_f32_e32 v87, 1.0, v86
	v_add_f32_e32 v88, -1.0, v87
	v_frexp_mant_f32_e32 v89, v87
	v_cvt_f64_f32_e32 v[0:1], v87
	v_sub_f32_e32 v90, v88, v87
	v_frexp_exp_i32_f64_e32 v0, v[0:1]
	v_cmp_gt_f32_e32 vcc, s4, v89
	v_sub_f32_e32 v88, v86, v88
	v_add_f32_e32 v1, 1.0, v90
	v_subbrev_co_u32_e32 v0, vcc, 0, v0, vcc
	v_add_f32_e32 v1, v88, v1
	v_sub_u32_e32 v88, 0, v0
	v_cvt_f32_i32_e32 v0, v0
	v_ldexp_f32 v87, v87, v88
	v_ldexp_f32 v1, v1, v88
	v_add_f32_e32 v88, -1.0, v87
	v_add_f32_e32 v89, 1.0, v87
	v_add_f32_e32 v90, 1.0, v88
	v_add_f32_e32 v91, -1.0, v89
	v_sub_f32_e32 v90, v87, v90
	v_sub_f32_e32 v87, v87, v91
	v_mul_f32_e32 v91, 0x3f317218, v0
	v_add_f32_e32 v90, v1, v90
	v_add_f32_e32 v1, v1, v87
	v_fma_f32 v87, v0, s5, -v91
	v_add_f32_e32 v92, v88, v90
	v_add_f32_e32 v93, v89, v1
	v_fmac_f32_e32 v87, 0xb102e308, v0
	v_sub_f32_e32 v0, v88, v92
	v_sub_f32_e32 v88, v89, v93
	v_rcp_f32_e32 v89, v93
	v_add_f32_e32 v94, v91, v87
	v_add_f32_e32 v1, v1, v88
	v_sub_f32_e32 v88, v94, v91
	v_sub_f32_e32 v87, v87, v88
	v_mul_f32_e32 v88, v92, v89
	v_add_f32_e32 v0, v90, v0
	v_mul_f32_e32 v90, v93, v88
	v_fma_f32 v91, v88, v93, -v90
	v_fmac_f32_e32 v91, v88, v1
	v_add_f32_e32 v95, v90, v91
	v_sub_f32_e32 v96, v92, v95
	v_sub_f32_e32 v90, v95, v90
	v_sub_f32_e32 v92, v92, v96
	v_sub_f32_e32 v90, v90, v91
	v_sub_f32_e32 v91, v92, v95
	v_add_f32_e32 v0, v0, v91
	v_add_f32_e32 v0, v90, v0
	v_add_f32_e32 v90, v96, v0
	v_mul_f32_e32 v91, v89, v90
	v_sub_f32_e32 v92, v96, v90
	v_mul_f32_e32 v95, v93, v91
	v_add_f32_e32 v0, v0, v92
	v_add_f32_e32 v92, v88, v91
	v_fma_f32 v93, v91, v93, -v95
	v_sub_f32_e32 v88, v92, v88
	v_fmac_f32_e32 v93, v91, v1
	v_sub_f32_e32 v1, v91, v88
	v_add_f32_e32 v88, v95, v93
	v_sub_f32_e32 v91, v88, v95
	v_sub_f32_e32 v95, v90, v88
	v_sub_f32_e32 v90, v90, v95
	v_sub_f32_e32 v88, v90, v88
	v_sub_f32_e32 v91, v91, v93
	v_add_f32_e32 v0, v0, v88
	v_add_f32_e32 v0, v91, v0
	v_add_f32_e32 v0, v95, v0
	v_mul_f32_e32 v0, v89, v0
	v_add_f32_e32 v0, v1, v0
	v_add_f32_e32 v1, v92, v0
	v_mul_f32_e32 v88, v1, v1
	v_fmamk_f32 v91, v88, 0x3e9b6dac, v62
	v_sub_f32_e32 v89, v1, v92
	v_ldexp_f32 v90, v1, 1
	v_mul_f32_e32 v1, v1, v88
	v_fmaak_f32 v88, v88, v91, 0x3f2aaada
	v_mul_f32_e32 v1, v1, v88
	v_add_f32_e32 v88, v90, v1
	v_sub_f32_e32 v0, v0, v89
	v_sub_f32_e32 v89, v88, v90
	v_ldexp_f32 v0, v0, 1
	v_sub_f32_e32 v1, v1, v89
	v_add_f32_e32 v0, v0, v1
	v_add_f32_e32 v1, v88, v0
	v_sub_f32_e32 v88, v1, v88
	v_add_f32_e32 v89, v94, v1
	v_sub_f32_e32 v0, v0, v88
	v_sub_f32_e32 v88, v89, v94
	v_sub_f32_e32 v90, v89, v88
	v_sub_f32_e32 v1, v1, v88
	v_add_f32_e32 v88, v87, v0
	v_sub_f32_e32 v90, v94, v90
	v_sub_f32_e32 v91, v88, v87
	v_add_f32_e32 v1, v1, v90
	v_sub_f32_e32 v90, v88, v91
	v_sub_f32_e32 v0, v0, v91
	v_sub_f32_e32 v87, v87, v90
	v_add_f32_e32 v1, v88, v1
	v_add_f32_e32 v0, v0, v87
	v_add_f32_e32 v87, v89, v1
	v_sub_f32_e32 v88, v87, v89
	v_sub_f32_e32 v1, v1, v88
	v_add_f32_e32 v0, v0, v1
	v_add_f32_e32 v0, v87, v0
	v_cmp_neq_f32_e32 vcc, s95, v86
	s_nop 1
	v_cndmask_b32_e32 v0, v63, v0, vcc
	v_cmp_lt_f32_e64 vcc, |v86|, s6
	s_nop 1
	v_cndmask_b32_e32 v0, v0, v86, vcc
	v_sub_f32_e32 v0, v85, v0
	ds_write_b32 v84, v0
	global_store_dword v33, v0, s[92:93]
.LBB0_39:
	s_or_b64 exec, exec, s[0:1]
	s_waitcnt vmcnt(61)
	v_mul_f32_e32 v0, v81, v81
	v_fmac_f32_e32 v0, v82, v82
	s_waitcnt vmcnt(60)
	v_fmac_f32_e32 v0, v80, v80
	s_waitcnt vmcnt(59)
	v_fmac_f32_e32 v0, v32, v32
	s_waitcnt vmcnt(58)
	v_fmac_f32_e32 v0, v31, v31
	s_waitcnt vmcnt(57)
	v_fmac_f32_e32 v0, v30, v30
	s_waitcnt vmcnt(56)
	v_fmac_f32_e32 v0, v29, v29
	s_waitcnt vmcnt(55)
	v_fmac_f32_e32 v0, v28, v28
	s_waitcnt vmcnt(54)
	v_fmac_f32_e32 v0, v27, v27
	s_waitcnt vmcnt(53)
	v_fmac_f32_e32 v0, v26, v26
	s_waitcnt vmcnt(52)
	v_fmac_f32_e32 v0, v25, v25
	s_waitcnt vmcnt(51)
	v_fmac_f32_e32 v0, v24, v24
	s_waitcnt vmcnt(50)
	v_fmac_f32_e32 v0, v23, v23
	s_waitcnt vmcnt(49)
	v_fmac_f32_e32 v0, v22, v22
	s_waitcnt vmcnt(48)
	v_fmac_f32_e32 v0, v21, v21
	v_fmac_f32_e32 v0, v20, v20
	ds_bpermute_b32 v1, v2, v0
	s_or_b32 s10, s10, 3
	s_add_i32 s92, s10, s45
	s_ashr_i32 s93, s92, 31
	s_lshl_b64 s[12:13], s[92:93], 11
	s_waitcnt lgkmcnt(0)
	v_add_f32_e32 v0, v0, v1
	ds_bpermute_b32 v1, v3, v0
	s_waitcnt lgkmcnt(0)
	v_add_f32_e32 v0, v0, v1
	ds_bpermute_b32 v1, v4, v0
	s_waitcnt lgkmcnt(0)
	v_add_f32_e32 v0, v0, v1
	ds_bpermute_b32 v1, v17, v0
	s_waitcnt lgkmcnt(0)
	v_add_f32_e32 v0, v0, v1
	ds_bpermute_b32 v1, v18, v0
	s_waitcnt lgkmcnt(0)
	v_add_f32_e32 v0, v0, v1
	ds_bpermute_b32 v1, v19, v0
	s_waitcnt lgkmcnt(0)
; #define LAS __attribute__((address_space(3)))
; __device__ __forceinline__ unsigned cvt_pk_bf16(float lo, float hi) { unsigned r; asm volatile("v_cvt_pk_bf16_f32 %0, %1, %2" : "=v"(r) : "v"(lo), "v"(hi)); return r; }
; __device__ __forceinline__ void p0_phase(const Args& a, LAS unsigned char* lds, int tid, int lane, int wave) {
;     ...
;                 const float rstd = 1.0f / sqrtf(wave_sum(ss) * (1.f / D) + EPS);
;                 float f[16];
; #pragma unroll
;                 for (int h = 0; h < 16; ++h) f[h] = 0.f;
; #pragma unroll
;                 for (int j = 0; j < 16; ++j) { const float xn = xa[u][j] * rstd * gm[j];
;                     XN[(size_t)row * D + lane + 64 * j] = (bf16_t)(cvt_pk_bf16(xn, 0.f) & 0xffffu);
;                     const LAS f32x4* wp = (const LAS f32x4*)(wfl + (lane + 64 * j) * 16);
; #pragma unroll
;                     for (int q = 0; q < 4; ++q) { const f32x4 w = wp[q]; f[4 * q + 0] += xn * w[0]; f[4 * q + 1] += xn * w[1]; f[4 * q + 2] += xn * w[2]; f[4 * q + 3] += xn * w[3]; } }
	v_add_f32_e32 v0, v0, v1
	v_fmamk_f32 v0, v0, 0x3a800000, v60
	v_mul_f32_e32 v1, 0x4f800000, v0
	v_cmp_gt_f32_e32 vcc, s49, v0
	s_nop 1
	v_cndmask_b32_e32 v0, v0, v1, vcc
	v_sqrt_f32_e32 v1, v0
	s_nop 0
	v_add_u32_e32 v84, -1, v1
	v_add_u32_e32 v85, 1, v1
	v_fma_f32 v86, -v84, v1, v0
	v_fma_f32 v87, -v85, v1, v0
	v_cmp_ge_f32_e64 s[0:1], 0, v86
	s_nop 1
	v_cndmask_b32_e64 v1, v1, v84, s[0:1]
	v_cmp_lt_f32_e64 s[0:1], 0, v87
	s_nop 1
	v_cndmask_b32_e64 v1, v1, v85, s[0:1]
	v_mul_f32_e32 v84, 0x37800000, v1
	v_cndmask_b32_e32 v1, v1, v84, vcc
	v_cmp_class_f32_e32 vcc, v0, v61
	s_nop 1
	v_cndmask_b32_e32 v84, v1, v0, vcc
	v_div_scale_f32 v85, s[0:1], v84, v84, 1.0
	v_rcp_f32_e32 v86, v85
	v_div_scale_f32 v87, vcc, 1.0, v84, 1.0
	v_lshl_add_u64 v[0:1], v[6:7], 0, s[12:13]
	v_fma_f32 v88, -v85, v86, 1.0
	v_fmac_f32_e32 v86, v88, v86
	v_mul_f32_e32 v88, v87, v86
	v_fma_f32 v89, -v85, v88, v87
	v_fmac_f32_e32 v88, v89, v86
	v_fma_f32 v85, -v85, v88, v87
	v_div_fmas_f32 v85, v85, v86, v88
	v_div_fixup_f32 v98, v85, v84, 1.0
	v_mul_f32_e32 v82, v82, v98
	v_mul_f32_e32 v99, v9, v82
	v_cvt_pk_bf16_f32 v82, v99, v5
	v_mul_f32_e32 v81, v81, v98
	global_store_short v[0:1], v82, off
	s_waitcnt lgkmcnt(0)
	v_fma_f32 v96, v160, v99, 0
	v_fma_f32 v92, v161, v99, 0
	v_fma_f32 v91, v162, v99, 0
	v_fma_f32 v90, v163, v99, 0
	s_waitcnt lgkmcnt(0)
	v_fma_f32 v86, v164, v99, 0
	v_fma_f32 v85, v165, v99, 0
	v_fma_f32 v84, v166, v99, 0
	v_fma_f32 v82, v167, v99, 0
	s_waitcnt lgkmcnt(0)
	v_fma_f32 v97, v168, v99, 0
	v_fma_f32 v95, v169, v99, 0
	v_fma_f32 v94, v170, v99, 0
	v_fma_f32 v93, v171, v99, 0
	s_waitcnt lgkmcnt(0)
	v_fma_f32 v89, v99, v172, 0
	v_fma_f32 v88, v99, v173, 0
	v_fma_f32 v87, v99, v174, 0
	v_fma_f32 v83, v99, v175, 0
	v_mul_f32_e32 v81, v34, v81
	v_cvt_pk_bf16_f32 v99, v81, v5
	global_store_short v[0:1], v99, off offset:128
	v_mul_f32_e32 v80, v80, v98
	v_mul_f32_e32 v80, v35, v80
	s_waitcnt lgkmcnt(0)
	v_fmac_f32_e32 v86, v81, v180
	v_fmac_f32_e32 v96, v81, v176
	v_fmac_f32_e32 v92, v81, v177
	v_fmac_f32_e32 v91, v81, v178
	v_fmac_f32_e32 v90, v81, v179
	v_fmac_f32_e32 v85, v81, v181
	v_fmac_f32_e32 v84, v81, v182
	v_fmac_f32_e32 v82, v81, v183
	s_waitcnt lgkmcnt(0)
	v_fmac_f32_e32 v97, v81, v184
	v_fmac_f32_e32 v95, v81, v185
	v_fmac_f32_e32 v94, v81, v186
	v_fmac_f32_e32 v93, v81, v187
	s_waitcnt lgkmcnt(0)
	v_fmac_f32_e32 v89, v81, v188
	v_fmac_f32_e32 v88, v81, v189
	v_fmac_f32_e32 v87, v81, v190
	v_fmac_f32_e32 v83, v81, v191
	v_cvt_pk_bf16_f32 v81, v80, v5
	global_store_short v[0:1], v81, off offset:256
	v_mul_f32_e32 v32, v32, v98
	v_mul_f32_e32 v32, v36, v32
	s_waitcnt lgkmcnt(0)
	v_fmac_f32_e32 v86, v80, v196
	v_fmac_f32_e32 v96, v80, v192
	v_fmac_f32_e32 v92, v80, v193
	v_fmac_f32_e32 v91, v80, v194
	v_fmac_f32_e32 v90, v80, v195
	v_fmac_f32_e32 v85, v80, v197
	v_fmac_f32_e32 v84, v80, v198
	v_fmac_f32_e32 v82, v80, v199
	s_waitcnt lgkmcnt(0)
	v_fmac_f32_e32 v97, v80, v200
	v_fmac_f32_e32 v95, v80, v201
	v_fmac_f32_e32 v94, v80, v202
	v_fmac_f32_e32 v93, v80, v203
	s_waitcnt lgkmcnt(0)
	v_fmac_f32_e32 v89, v80, v204
	v_fmac_f32_e32 v88, v80, v205
	v_fmac_f32_e32 v87, v80, v206
	v_fmac_f32_e32 v83, v80, v207
	v_cvt_pk_bf16_f32 v80, v32, v5
	global_store_short v[0:1], v80, off offset:384
	v_mul_f32_e32 v31, v31, v98
	v_mul_f32_e32 v31, v37, v31
	s_waitcnt lgkmcnt(0)
	v_fmac_f32_e32 v86, v32, v212
	v_fmac_f32_e32 v96, v32, v208
	v_fmac_f32_e32 v92, v32, v209
	v_fmac_f32_e32 v91, v32, v210
	v_fmac_f32_e32 v90, v32, v211
	v_fmac_f32_e32 v85, v32, v213
	v_fmac_f32_e32 v84, v32, v214
	v_fmac_f32_e32 v82, v32, v215
	s_waitcnt lgkmcnt(0)
	v_fmac_f32_e32 v97, v32, v216
	v_fmac_f32_e32 v95, v32, v217
	v_fmac_f32_e32 v94, v32, v218
	v_fmac_f32_e32 v93, v32, v219
	s_waitcnt lgkmcnt(0)
	v_fmac_f32_e32 v89, v32, v220
	v_fmac_f32_e32 v88, v32, v221
	v_fmac_f32_e32 v87, v32, v222
	v_fmac_f32_e32 v83, v32, v223
	v_cvt_pk_bf16_f32 v32, v31, v5
	global_store_short v[0:1], v32, off offset:512
	v_mul_f32_e32 v30, v30, v98
	v_mul_f32_e32 v30, v38, v30
	s_waitcnt lgkmcnt(0)
	v_fmac_f32_e32 v86, v31, v228
	v_fmac_f32_e32 v96, v31, v224
	v_fmac_f32_e32 v92, v31, v225
	v_fmac_f32_e32 v91, v31, v226
	v_fmac_f32_e32 v90, v31, v227
	v_fmac_f32_e32 v85, v31, v229
	v_fmac_f32_e32 v84, v31, v230
	v_fmac_f32_e32 v82, v31, v231
	s_waitcnt lgkmcnt(0)
	v_fmac_f32_e32 v97, v31, v232
	v_fmac_f32_e32 v95, v31, v233
	v_fmac_f32_e32 v94, v31, v234
	v_fmac_f32_e32 v93, v31, v235
	s_waitcnt lgkmcnt(0)
	v_fmac_f32_e32 v89, v31, v236
	v_fmac_f32_e32 v88, v31, v237
	v_fmac_f32_e32 v87, v31, v238
	v_fmac_f32_e32 v83, v31, v239
	v_cvt_pk_bf16_f32 v31, v30, v5
	global_store_short v[0:1], v31, off offset:640
	ds_read_b128 v[112:115], v69 offset:48
	v_mul_f32_e32 v29, v29, v98
	v_mul_f32_e32 v29, v39, v29
	s_waitcnt lgkmcnt(1)
	v_fmac_f32_e32 v86, v30, v244
	v_fmac_f32_e32 v96, v30, v240
	v_fmac_f32_e32 v92, v30, v241
	v_fmac_f32_e32 v91, v30, v242
	v_fmac_f32_e32 v90, v30, v243
	v_fmac_f32_e32 v85, v30, v245
	v_fmac_f32_e32 v84, v30, v246
	v_fmac_f32_e32 v82, v30, v247
	s_waitcnt lgkmcnt(1)
	v_fmac_f32_e32 v97, v30, v248
	v_fmac_f32_e32 v95, v30, v249
	v_fmac_f32_e32 v94, v30, v250
	v_fmac_f32_e32 v93, v30, v251
	s_waitcnt lgkmcnt(0)
	v_fmac_f32_e32 v89, v30, v112
	v_fmac_f32_e32 v88, v30, v113
	v_fmac_f32_e32 v87, v30, v114
	v_fmac_f32_e32 v83, v30, v115
	v_cvt_pk_bf16_f32 v30, v29, v5
	global_store_short v[0:1], v30, off offset:768
	ds_read_b128 v[100:103], v70
	ds_read_b128 v[104:107], v70 offset:16
	ds_read_b128 v[108:111], v70 offset:32
	ds_read_b128 v[112:115], v70 offset:48
	v_mul_f32_e32 v28, v28, v98
	v_mul_f32_e32 v32, v40, v28
	v_cvt_pk_bf16_f32 v80, v32, v5
	global_store_short v[0:1], v80, off offset:896
	s_waitcnt lgkmcnt(3)
; #define LAS __attribute__((address_space(3)))
; __device__ __forceinline__ unsigned cvt_pk_bf16(float lo, float hi) { unsigned r; asm volatile("v_cvt_pk_bf16_f32 %0, %1, %2" : "=v"(r) : "v"(lo), "v"(hi)); return r; }
; __device__ __forceinline__ void p0_phase(const Args& a, LAS unsigned char* lds, int tid, int lane, int wave) {
;     ...
;                 for (int j = 0; j < 16; ++j) { const float xn = xa[u][j] * rstd * gm[j];
;                     XN[(size_t)row * D + lane + 64 * j] = (bf16_t)(cvt_pk_bf16(xn, 0.f) & 0xffffu);
;                     const LAS f32x4* wp = (const LAS f32x4*)(wfl + (lane + 64 * j) * 16);
; #pragma unroll
;                     for (int q = 0; q < 4; ++q) { const f32x4 w = wp[q]; f[4 * q + 0] += xn * w[0]; f[4 * q + 1] += xn * w[1]; f[4 * q + 2] += xn * w[2]; f[4 * q + 3] += xn * w[3]; } }
	v_fmac_f32_e32 v96, v29, v100
	v_fmac_f32_e32 v92, v29, v101
	v_fmac_f32_e32 v91, v29, v102
	v_fmac_f32_e32 v90, v29, v103
	s_waitcnt lgkmcnt(2)
	v_fmac_f32_e32 v86, v29, v104
	v_fmac_f32_e32 v85, v29, v105
	v_fmac_f32_e32 v84, v29, v106
	v_fmac_f32_e32 v82, v29, v107
	s_waitcnt lgkmcnt(1)
	v_fmac_f32_e32 v97, v29, v108
	v_fmac_f32_e32 v95, v29, v109
	v_fmac_f32_e32 v94, v29, v110
	v_fmac_f32_e32 v93, v29, v111
	s_waitcnt lgkmcnt(0)
	v_fmac_f32_e32 v89, v29, v112
	v_fmac_f32_e32 v88, v29, v113
	v_fmac_f32_e32 v87, v29, v114
	v_fmac_f32_e32 v83, v29, v115
	ds_read_b128 v[28:31], v71
	ds_read_b128 v[100:103], v71 offset:16
	ds_read_b128 v[104:107], v71 offset:32
	ds_read_b128 v[108:111], v71 offset:48
	v_mul_f32_e32 v27, v27, v98
	v_mul_f32_e32 v27, v41, v27
	s_waitcnt lgkmcnt(2)
	v_fmac_f32_e32 v86, v32, v100
	v_fmac_f32_e32 v96, v32, v28
	v_fmac_f32_e32 v92, v32, v29
	v_fmac_f32_e32 v91, v32, v30
	v_fmac_f32_e32 v90, v32, v31
	v_fmac_f32_e32 v85, v32, v101
	v_fmac_f32_e32 v84, v32, v102
	v_fmac_f32_e32 v82, v32, v103
	s_waitcnt lgkmcnt(1)
	v_fmac_f32_e32 v97, v32, v104
	v_fmac_f32_e32 v95, v32, v105
	v_fmac_f32_e32 v94, v32, v106
	v_fmac_f32_e32 v93, v32, v107
	s_waitcnt lgkmcnt(0)
	v_fmac_f32_e32 v89, v32, v108
	v_fmac_f32_e32 v88, v32, v109
	v_fmac_f32_e32 v87, v32, v110
	v_fmac_f32_e32 v83, v32, v111
	v_cvt_pk_bf16_f32 v32, v27, v5
	ds_read_b128 v[28:31], v72
	global_store_short v[0:1], v32, off offset:1024
	ds_read_b128 v[100:103], v72 offset:16
	ds_read_b128 v[104:107], v72 offset:32
	ds_read_b128 v[108:111], v72 offset:48
	v_mul_f32_e32 v26, v26, v98
	v_mul_f32_e32 v25, v25, v98
	s_waitcnt lgkmcnt(3)
	v_fmac_f32_e32 v91, v27, v30
	v_fmac_f32_e32 v90, v27, v31
	v_mul_f32_e32 v30, v42, v26
	v_cvt_pk_bf16_f32 v31, v30, v5
	global_store_short v[0:1], v31, off offset:1152
	v_fmac_f32_e32 v96, v27, v28
	v_fmac_f32_e32 v92, v27, v29
	s_waitcnt lgkmcnt(2)
	v_fmac_f32_e32 v86, v27, v100
	v_fmac_f32_e32 v85, v27, v101
	v_fmac_f32_e32 v84, v27, v102
	v_fmac_f32_e32 v82, v27, v103
	s_waitcnt lgkmcnt(1)
	v_fmac_f32_e32 v97, v27, v104
	v_fmac_f32_e32 v95, v27, v105
	v_fmac_f32_e32 v94, v27, v106
	v_fmac_f32_e32 v93, v27, v107
	s_waitcnt lgkmcnt(0)
	v_fmac_f32_e32 v89, v27, v108
	v_fmac_f32_e32 v88, v27, v109
	v_fmac_f32_e32 v87, v27, v110
	v_fmac_f32_e32 v83, v27, v111
	ds_read_b128 v[26:29], v73
	ds_read_b128 v[100:103], v73 offset:16
	ds_read_b128 v[104:107], v73 offset:32
	ds_read_b128 v[108:111], v73 offset:48
	v_mul_f32_e32 v25, v43, v25
	v_mul_f32_e32 v24, v24, v98
	s_waitcnt lgkmcnt(2)
	v_fmac_f32_e32 v86, v30, v100
	v_fmac_f32_e32 v96, v30, v26
	v_fmac_f32_e32 v92, v30, v27
	v_fmac_f32_e32 v91, v30, v28
	v_fmac_f32_e32 v90, v30, v29
	v_fmac_f32_e32 v85, v30, v101
	v_fmac_f32_e32 v84, v30, v102
	v_fmac_f32_e32 v82, v30, v103
	s_waitcnt lgkmcnt(1)
	v_fmac_f32_e32 v97, v30, v104
	v_fmac_f32_e32 v95, v30, v105
	v_fmac_f32_e32 v94, v30, v106
	v_fmac_f32_e32 v93, v30, v107
	s_waitcnt lgkmcnt(0)
	v_fmac_f32_e32 v89, v30, v108
	v_fmac_f32_e32 v88, v30, v109
	v_fmac_f32_e32 v87, v30, v110
	v_fmac_f32_e32 v83, v30, v111
	v_cvt_pk_bf16_f32 v30, v25, v5
	global_store_short v[0:1], v30, off offset:1280
	ds_read_b128 v[26:29], v74
	ds_read_b128 v[100:103], v74 offset:16
	ds_read_b128 v[104:107], v74 offset:32
	ds_read_b128 v[108:111], v74 offset:48
	v_mul_f32_e32 v32, v44, v24
	v_mul_f32_e32 v23, v23, v98
	s_waitcnt lgkmcnt(2)
	v_fmac_f32_e32 v86, v25, v100
	v_fmac_f32_e32 v96, v25, v26
	v_fmac_f32_e32 v92, v25, v27
	v_fmac_f32_e32 v91, v25, v28
	v_fmac_f32_e32 v90, v25, v29
	v_fmac_f32_e32 v85, v25, v101
	v_fmac_f32_e32 v84, v25, v102
	v_fmac_f32_e32 v82, v25, v103
	s_waitcnt lgkmcnt(1)
	v_fmac_f32_e32 v97, v25, v104
	v_fmac_f32_e32 v95, v25, v105
	v_fmac_f32_e32 v94, v25, v106
	v_fmac_f32_e32 v93, v25, v107
	s_waitcnt lgkmcnt(0)
	v_fmac_f32_e32 v89, v25, v108
	v_fmac_f32_e32 v88, v25, v109
	v_fmac_f32_e32 v87, v25, v110
	v_fmac_f32_e32 v83, v25, v111
	v_cvt_pk_bf16_f32 v28, v32, v5
	ds_read_b128 v[24:27], v75
	global_store_short v[0:1], v28, off offset:1408
	ds_read_b128 v[28:31], v75 offset:16
	ds_read_b128 v[100:103], v75 offset:32
	ds_read_b128 v[104:107], v75 offset:48
	v_mul_f32_e32 v23, v45, v23
	v_mul_f32_e32 v22, v22, v98
	s_waitcnt lgkmcnt(3)
	v_fmac_f32_e32 v96, v32, v24
	v_fmac_f32_e32 v92, v32, v25
	v_fmac_f32_e32 v91, v32, v26
	v_fmac_f32_e32 v90, v32, v27
	s_waitcnt lgkmcnt(2)
	v_fmac_f32_e32 v86, v32, v28
	v_cvt_pk_bf16_f32 v28, v23, v5
	ds_read_b128 v[24:27], v76
	global_store_short v[0:1], v28, off offset:1536
	v_fmac_f32_e32 v85, v32, v29
	v_fmac_f32_e32 v84, v32, v30
	v_fmac_f32_e32 v82, v32, v31
	s_waitcnt lgkmcnt(2)
	v_fmac_f32_e32 v97, v32, v100
	v_fmac_f32_e32 v95, v32, v101
	v_fmac_f32_e32 v94, v32, v102
	v_fmac_f32_e32 v93, v32, v103
	s_waitcnt lgkmcnt(1)
	v_fmac_f32_e32 v89, v32, v104
	v_fmac_f32_e32 v88, v32, v105
	v_fmac_f32_e32 v87, v32, v106
	v_fmac_f32_e32 v83, v32, v107
	ds_read_b128 v[28:31], v76 offset:16
	ds_read_b128 v[100:103], v76 offset:32
	ds_read_b128 v[104:107], v76 offset:48
	s_waitcnt lgkmcnt(3)
	v_fmac_f32_e32 v91, v23, v26
	v_fmac_f32_e32 v96, v23, v24
	s_waitcnt lgkmcnt(2)
	v_fmac_f32_e32 v84, v23, v30
	v_mul_f32_e32 v30, v46, v22
	v_cvt_pk_bf16_f32 v26, v30, v5
	global_store_short v[0:1], v26, off offset:1664
	v_fmac_f32_e32 v92, v23, v25
	v_fmac_f32_e32 v90, v23, v27
	v_fmac_f32_e32 v86, v23, v28
	v_fmac_f32_e32 v85, v23, v29
	v_fmac_f32_e32 v82, v23, v31
	s_waitcnt lgkmcnt(1)
	v_fmac_f32_e32 v97, v23, v100
	v_fmac_f32_e32 v95, v23, v101
	v_fmac_f32_e32 v94, v23, v102
	v_fmac_f32_e32 v93, v23, v103
	s_waitcnt lgkmcnt(0)
; #define LAS __attribute__((address_space(3)))
; __device__ __forceinline__ unsigned cvt_pk_bf16(float lo, float hi) { unsigned r; asm volatile("v_cvt_pk_bf16_f32 %0, %1, %2" : "=v"(r) : "v"(lo), "v"(hi)); return r; }
; __device__ __forceinline__ void p0_phase(const Args& a, LAS unsigned char* lds, int tid, int lane, int wave) {
;     ...
;                 for (int j = 0; j < 16; ++j) { const float xn = xa[u][j] * rstd * gm[j];
;                     XN[(size_t)row * D + lane + 64 * j] = (bf16_t)(cvt_pk_bf16(xn, 0.f) & 0xffffu);
;                     const LAS f32x4* wp = (const LAS f32x4*)(wfl + (lane + 64 * j) * 16);
; #pragma unroll
;                     for (int q = 0; q < 4; ++q) { const f32x4 w = wp[q]; f[4 * q + 0] += xn * w[0]; f[4 * q + 1] += xn * w[1]; f[4 * q + 2] += xn * w[2]; f[4 * q + 3] += xn * w[3]; } }
;                 { const bool b5 = lane & 32;
; #pragma unroll
;                   for (int k = 0; k < 8; ++k) { const float send = b5 ? f[k] : f[k + 8], keep = b5 ? f[k + 8] : f[k]; f[k] = keep + __shfl_xor(send, 32); }
;                   const bool b4 = lane & 16;
; #pragma unroll
;                   for (int k = 0; k < 4; ++k) { const float send = b4 ? f[k] : f[k + 4], keep = b4 ? f[k + 4] : f[k]; f[k] = keep + __shfl_xor(send, 16); }
;                   const bool b3 = lane & 8;
; #pragma unroll
;                   for (int k = 0; k < 2; ++k) { const float send = b3 ? f[k] : f[k + 2], keep = b3 ? f[k + 2] : f[k]; f[k] = keep + __shfl_xor(send, 8); }
;                   const bool b2 = lane & 4;
;                   { const float send = b2 ? f[0] : f[1], keep = b2 ? f[1] : f[0]; f[0] = keep + __shfl_xor(send, 4); }
;                   f[0] += __shfl_xor(f[0], 2); f[0] += __shfl_xor(f[0], 1); }
;                 if ((lane & 3) == 0) { const int hh = ((lane >> 5) & 1) * 8 + ((lane >> 4) & 1) * 4 + ((lane >> 3) & 1) * 2 + ((lane >> 2) & 1);
	v_fmac_f32_e32 v89, v23, v104
	v_fmac_f32_e32 v88, v23, v105
	v_fmac_f32_e32 v87, v23, v106
	v_fmac_f32_e32 v83, v23, v107
	ds_read_b128 v[22:25], v77
	ds_read_b128 v[26:29], v77 offset:16
	ds_read_b128 v[100:103], v77 offset:32
	ds_read_b128 v[104:107], v77 offset:48
	v_mul_f32_e32 v21, v21, v98
	v_mul_f32_e32 v20, v20, v98
	s_waitcnt lgkmcnt(2)
	v_fmac_f32_e32 v86, v30, v26
	v_fmac_f32_e32 v96, v30, v22
	v_fmac_f32_e32 v92, v30, v23
	v_fmac_f32_e32 v91, v30, v24
	v_fmac_f32_e32 v90, v30, v25
	v_fmac_f32_e32 v85, v30, v27
	v_fmac_f32_e32 v84, v30, v28
	v_fmac_f32_e32 v82, v30, v29
	s_waitcnt lgkmcnt(1)
	v_fmac_f32_e32 v97, v30, v100
	v_fmac_f32_e32 v95, v30, v101
	v_fmac_f32_e32 v94, v30, v102
	v_fmac_f32_e32 v93, v30, v103
	s_waitcnt lgkmcnt(0)
	v_fmac_f32_e32 v89, v30, v104
	v_fmac_f32_e32 v88, v30, v105
	v_fmac_f32_e32 v87, v30, v106
	v_fmac_f32_e32 v83, v30, v107
	v_mul_f32_e32 v30, v47, v21
	v_cvt_pk_bf16_f32 v21, v30, v5
	ds_read_b128 v[22:25], v78
	global_store_short v[0:1], v21, off offset:1792
	ds_read_b128 v[26:29], v78 offset:16
	ds_read_b128 v[100:103], v78 offset:32
	ds_read_b128 v[104:107], v78 offset:48
	v_mul_f32_e32 v32, v48, v20
	v_cvt_pk_bf16_f32 v80, v32, v5
	s_waitcnt lgkmcnt(3)
	v_fmac_f32_e32 v96, v30, v22
	v_fmac_f32_e32 v92, v30, v23
	ds_read_b128 v[20:23], v79
	v_fmac_f32_e32 v91, v30, v24
	v_fmac_f32_e32 v90, v30, v25
	s_waitcnt lgkmcnt(3)
	v_fmac_f32_e32 v86, v30, v26
	v_fmac_f32_e32 v85, v30, v27
	v_fmac_f32_e32 v84, v30, v28
	v_fmac_f32_e32 v82, v30, v29
	s_waitcnt lgkmcnt(2)
	v_fmac_f32_e32 v97, v30, v100
	v_fmac_f32_e32 v95, v30, v101
	v_fmac_f32_e32 v94, v30, v102
	v_fmac_f32_e32 v93, v30, v103
	s_waitcnt lgkmcnt(1)
	v_fmac_f32_e32 v89, v30, v104
	v_fmac_f32_e32 v88, v30, v105
	v_fmac_f32_e32 v87, v30, v106
	v_fmac_f32_e32 v83, v30, v107
	ds_read_b128 v[24:27], v79 offset:16
	ds_read_b128 v[28:31], v79 offset:32
	ds_read_b128 v[98:101], v79 offset:48
	s_waitcnt lgkmcnt(3)
	v_fmac_f32_e32 v96, v32, v20
	v_fmac_f32_e32 v92, v32, v21
	v_fmac_f32_e32 v91, v32, v22
	s_waitcnt lgkmcnt(1)
	v_fmac_f32_e32 v97, v32, v28
	v_fmac_f32_e32 v95, v32, v29
	v_cndmask_b32_e64 v20, v96, v97, s[26:27]
	v_fmac_f32_e32 v94, v32, v30
	ds_bpermute_b32 v20, v19, v20
	v_cndmask_b32_e64 v22, v92, v95, s[26:27]
	v_fmac_f32_e32 v90, v32, v23
	ds_bpermute_b32 v22, v19, v22
	v_cndmask_b32_e64 v23, v91, v94, s[26:27]
	ds_bpermute_b32 v23, v19, v23
	v_cndmask_b32_e64 v21, v97, v96, s[26:27]
	s_waitcnt lgkmcnt(2)
	v_add_f32_e32 v20, v21, v20
	v_cndmask_b32_e64 v21, v95, v92, s[26:27]
	v_fmac_f32_e32 v93, v32, v31
	s_waitcnt lgkmcnt(1)
	v_add_f32_e32 v21, v21, v22
	v_cndmask_b32_e64 v22, v94, v91, s[26:27]
	v_fmac_f32_e32 v86, v32, v24
	v_fmac_f32_e32 v89, v32, v98
	s_waitcnt lgkmcnt(0)
	v_add_f32_e32 v22, v22, v23
	v_cndmask_b32_e64 v23, v90, v93, s[26:27]
	v_fmac_f32_e32 v85, v32, v25
	v_fmac_f32_e32 v88, v32, v99
	ds_bpermute_b32 v23, v19, v23
	v_cndmask_b32_e64 v25, v86, v89, s[26:27]
	v_fmac_f32_e32 v84, v32, v26
	ds_bpermute_b32 v25, v19, v25
	v_cndmask_b32_e64 v26, v85, v88, s[26:27]
	ds_bpermute_b32 v26, v19, v26
	v_cndmask_b32_e64 v24, v93, v90, s[26:27]
	s_waitcnt lgkmcnt(2)
	v_add_f32_e32 v23, v24, v23
	v_cndmask_b32_e64 v24, v89, v86, s[26:27]
	v_fmac_f32_e32 v87, v32, v100
	s_waitcnt lgkmcnt(1)
	v_add_f32_e32 v24, v24, v25
	v_cndmask_b32_e64 v25, v88, v85, s[26:27]
	v_fmac_f32_e32 v82, v32, v27
	v_fmac_f32_e32 v83, v32, v101
	s_waitcnt lgkmcnt(0)
	v_add_f32_e32 v25, v25, v26
	v_cndmask_b32_e64 v26, v84, v87, s[26:27]
	ds_bpermute_b32 v26, v19, v26
	v_cndmask_b32_e64 v28, v82, v83, s[26:27]
	ds_bpermute_b32 v28, v19, v28
	v_cndmask_b32_e64 v27, v87, v84, s[26:27]
	v_cndmask_b32_e64 v29, v20, v24, s[28:29]
	s_waitcnt lgkmcnt(1)
	v_add_f32_e32 v26, v27, v26
	v_cndmask_b32_e64 v27, v83, v82, s[26:27]
	s_waitcnt lgkmcnt(0)
	v_add_f32_e32 v27, v27, v28
	v_cndmask_b32_e64 v20, v24, v20, s[28:29]
	v_cndmask_b32_e64 v24, v21, v25, s[28:29]
	v_cndmask_b32_e64 v21, v25, v21, s[28:29]
	v_cndmask_b32_e64 v25, v22, v26, s[28:29]
	v_cndmask_b32_e64 v28, v23, v27, s[28:29]
	ds_bpermute_b32 v29, v18, v29
	ds_bpermute_b32 v24, v18, v24
	ds_bpermute_b32 v25, v18, v25
	ds_bpermute_b32 v28, v18, v28
	v_cndmask_b32_e64 v22, v26, v22, s[28:29]
	v_cndmask_b32_e64 v23, v27, v23, s[28:29]
	s_waitcnt lgkmcnt(3)
	v_add_f32_e32 v20, v20, v29
	s_waitcnt lgkmcnt(2)
	v_add_f32_e32 v21, v21, v24
	s_waitcnt lgkmcnt(1)
	v_add_f32_e32 v22, v22, v25
	s_waitcnt lgkmcnt(0)
	v_add_f32_e32 v23, v23, v28
	v_cndmask_b32_e64 v24, v20, v22, s[30:31]
	v_cndmask_b32_e64 v25, v21, v23, s[30:31]
	ds_bpermute_b32 v24, v17, v24
	ds_bpermute_b32 v25, v17, v25
	v_cndmask_b32_e64 v20, v22, v20, s[30:31]
	v_cndmask_b32_e64 v21, v23, v21, s[30:31]
	global_store_short v[0:1], v80, off offset:1920
	s_waitcnt lgkmcnt(1)
	v_add_f32_e32 v20, v20, v24
	s_waitcnt lgkmcnt(0)
	v_add_f32_e32 v21, v21, v25
	v_cndmask_b32_e64 v22, v20, v21, s[34:35]
	ds_bpermute_b32 v22, v4, v22
	v_cndmask_b32_e64 v20, v21, v20, s[34:35]
	s_waitcnt lgkmcnt(0)
	v_add_f32_e32 v20, v20, v22
	ds_bpermute_b32 v21, v3, v20
	s_waitcnt lgkmcnt(0)
	v_add_f32_e32 v20, v20, v21
	ds_bpermute_b32 v21, v2, v20
	s_and_saveexec_b64 s[0:1], s[36:37]
	s_cbranch_execz .LBB0_32
; __device__ __forceinline__ void p0_phase(const Args& a, LAS unsigned char* lds, int tid, int lane, int wave) {
;     ...
;                 if ((lane & 3) == 0) { const int hh = ((lane >> 5) & 1) * 8 + ((lane >> 4) & 1) * 4 + ((lane >> 3) & 1) * 2 + ((lane >> 2) & 1);
;                     const float z = f[0] + bfg[hh]; const float lg = fminf(z, 0.f) - log1pf(expf(-fabsf(z)));
;                     lf[rl * 16 + hh] = lg;
;                     if (row < MP) a.out[O_LFP + (size_t)row * NH + hh] = lg; else a.out[O_LFS + (size_t)(row - MP) * NH + hh] = lg; }
	global_load_dword v0, v[10:11], off
	s_waitcnt lgkmcnt(0)
	v_add_f32_e32 v1, v20, v21
	v_lshl_add_u32 v20, s10, 6, v51
	s_add_i32 s10, s92, 0xffffc000
	s_cmpk_lt_i32 s92, 0x4000
	s_cselect_b32 s11, s93, 0
	s_cselect_b32 s10, s92, s10
	s_cselect_b32 s12, s7, 0xcd04000
	s_lshl_b64 s[10:11], s[10:11], 6
	s_add_u32 s10, s86, s10
	s_addc_u32 s11, s87, s11
	s_add_u32 s92, s10, s12
	s_addc_u32 s93, s11, 0
	s_waitcnt vmcnt(0)
	v_add_f32_e32 v0, v1, v0
	v_mul_f32_e64 v1, |v0|, s70
	v_fma_f32 v21, |v0|, s70, -v1
	v_rndne_f32_e32 v22, v1
	v_fma_f32 v21, |v0|, s71, v21
	v_sub_f32_e32 v1, v1, v22
	v_add_f32_e32 v1, v1, v21
	v_cvt_i32_f32_e32 v22, v22
	v_exp_f32_e32 v1, v1
	v_cmp_ngt_f32_e64 vcc, |v0|, s50
	v_min_f32_e32 v21, 0, v0
	v_ldexp_f32 v1, v1, v22
	v_cndmask_b32_e32 v1, 0, v1, vcc
	v_cmp_nlt_f32_e64 vcc, |v0|, s94
	s_nop 1
	v_cndmask_b32_e32 v22, v63, v1, vcc
	v_add_f32_e32 v23, 1.0, v22
	v_add_f32_e32 v24, -1.0, v23
	v_frexp_mant_f32_e32 v25, v23
	v_cvt_f64_f32_e32 v[0:1], v23
	v_sub_f32_e32 v26, v24, v23
	v_frexp_exp_i32_f64_e32 v0, v[0:1]
	v_cmp_gt_f32_e32 vcc, s4, v25
	v_sub_f32_e32 v24, v22, v24
	v_add_f32_e32 v1, 1.0, v26
	v_subbrev_co_u32_e32 v0, vcc, 0, v0, vcc
	v_add_f32_e32 v1, v24, v1
	v_sub_u32_e32 v24, 0, v0
	v_cvt_f32_i32_e32 v0, v0
	v_ldexp_f32 v23, v23, v24
	v_ldexp_f32 v1, v1, v24
	v_add_f32_e32 v24, -1.0, v23
	v_add_f32_e32 v25, 1.0, v23
	v_add_f32_e32 v26, 1.0, v24
	v_add_f32_e32 v27, -1.0, v25
	v_sub_f32_e32 v26, v23, v26
	v_sub_f32_e32 v23, v23, v27
	v_mul_f32_e32 v27, 0x3f317218, v0
	v_add_f32_e32 v26, v1, v26
	v_add_f32_e32 v1, v1, v23
	v_fma_f32 v23, v0, s5, -v27
	v_add_f32_e32 v28, v24, v26
	v_add_f32_e32 v29, v25, v1
	v_fmac_f32_e32 v23, 0xb102e308, v0
	v_sub_f32_e32 v0, v24, v28
	v_sub_f32_e32 v24, v25, v29
	v_rcp_f32_e32 v25, v29
	v_add_f32_e32 v30, v27, v23
	v_add_f32_e32 v1, v1, v24
	v_sub_f32_e32 v24, v30, v27
	v_sub_f32_e32 v23, v23, v24
	v_mul_f32_e32 v24, v28, v25
	v_add_f32_e32 v0, v26, v0
	v_mul_f32_e32 v26, v29, v24
	v_fma_f32 v27, v24, v29, -v26
	v_fmac_f32_e32 v27, v24, v1
	v_add_f32_e32 v31, v26, v27
	v_sub_f32_e32 v32, v28, v31
	v_sub_f32_e32 v26, v31, v26
	v_sub_f32_e32 v28, v28, v32
	v_sub_f32_e32 v26, v26, v27
	v_sub_f32_e32 v27, v28, v31
	v_add_f32_e32 v0, v0, v27
	v_add_f32_e32 v0, v26, v0
	v_add_f32_e32 v26, v32, v0
	v_mul_f32_e32 v27, v25, v26
	v_sub_f32_e32 v28, v32, v26
	v_mul_f32_e32 v31, v29, v27
	v_add_f32_e32 v0, v0, v28
	v_add_f32_e32 v28, v24, v27
	v_fma_f32 v29, v27, v29, -v31
	v_sub_f32_e32 v24, v28, v24
	v_fmac_f32_e32 v29, v27, v1
	v_sub_f32_e32 v1, v27, v24
	v_add_f32_e32 v24, v31, v29
	v_sub_f32_e32 v27, v24, v31
	v_sub_f32_e32 v31, v26, v24
	v_sub_f32_e32 v26, v26, v31
	v_sub_f32_e32 v24, v26, v24
	v_sub_f32_e32 v27, v27, v29
	v_add_f32_e32 v0, v0, v24
	v_add_f32_e32 v0, v27, v0
	v_add_f32_e32 v0, v31, v0
	v_mul_f32_e32 v0, v25, v0
	v_add_f32_e32 v0, v1, v0
	v_add_f32_e32 v1, v28, v0
	v_mul_f32_e32 v24, v1, v1
	v_fmamk_f32 v27, v24, 0x3e9b6dac, v62
	v_sub_f32_e32 v25, v1, v28
	v_ldexp_f32 v26, v1, 1
	v_mul_f32_e32 v1, v1, v24
	v_fmaak_f32 v24, v24, v27, 0x3f2aaada
	v_mul_f32_e32 v1, v1, v24
	v_add_f32_e32 v24, v26, v1
	v_sub_f32_e32 v0, v0, v25
	v_sub_f32_e32 v25, v24, v26
	v_ldexp_f32 v0, v0, 1
	v_sub_f32_e32 v1, v1, v25
	v_add_f32_e32 v0, v0, v1
	v_add_f32_e32 v1, v24, v0
	v_sub_f32_e32 v24, v1, v24
	v_add_f32_e32 v25, v30, v1
	v_sub_f32_e32 v0, v0, v24
	v_sub_f32_e32 v24, v25, v30
	v_sub_f32_e32 v26, v25, v24
	v_sub_f32_e32 v1, v1, v24
	v_add_f32_e32 v24, v23, v0
	v_sub_f32_e32 v26, v30, v26
	v_sub_f32_e32 v27, v24, v23
	v_add_f32_e32 v1, v1, v26
	v_sub_f32_e32 v26, v24, v27
	v_sub_f32_e32 v0, v0, v27
	v_sub_f32_e32 v23, v23, v26
	v_add_f32_e32 v1, v24, v1
	v_add_f32_e32 v0, v0, v23
	v_add_f32_e32 v23, v25, v1
	v_sub_f32_e32 v24, v23, v25
	v_sub_f32_e32 v1, v1, v24
	v_add_f32_e32 v0, v0, v1
	v_add_f32_e32 v0, v23, v0
	v_cmp_neq_f32_e32 vcc, s95, v22
	s_nop 1
	v_cndmask_b32_e32 v0, v63, v0, vcc
	v_cmp_lt_f32_e64 vcc, |v22|, s6
	s_nop 1
	v_cndmask_b32_e32 v0, v0, v22, vcc
	v_sub_f32_e32 v0, v21, v0
	ds_write_b32 v20, v0
	global_store_dword v33, v0, s[92:93]
	s_branch .LBB0_32
